# non-temporal hint on the prologue's read-once f32 source loads (weights and x), on top of non-temporal streaming stores
# speedup vs baseline: 1.0049x; 1.0049x over previous
.LBB0_11:
	s_andn2_b64 vcc, exec, s[16:17]
	s_cbranch_vccnz .LBB0_13
	v_lshl_add_u32 v4, s18, 6, v64
	v_mov_b64_e32 v[2:3], s[14:15]
	v_mad_i64_i32 v[2:3], s[16:17], v4, s5, v[2:3]
	v_lshl_add_u64 v[2:3], s[8:9], 2, v[2:3]
	v_lshlrev_b32_e32 v130, 2, v62
	s_waitcnt vmcnt(9)
	v_lshl_add_u64 v[58:59], v[2:3], 0, v[130:131]
	v_add_co_u32_e32 v6, vcc, 0x2c000, v58
	v_mov_b32_e32 v63, v131
	s_nop 0
	v_addc_co_u32_e32 v7, vcc, 0, v59, vcc
	v_add_co_u32_e32 v10, vcc, 0x58000, v58
	global_load_dwordx4 v[2:5], v[58:59], off nt
	s_nop 0
	global_load_dwordx4 v[6:9], v[6:7], off nt
	v_addc_co_u32_e32 v11, vcc, 0, v59, vcc
	v_add_co_u32_e32 v14, vcc, 0x84000, v58
	v_mov_b64_e32 v[132:133], v[62:63]
	s_nop 0
	v_addc_co_u32_e32 v15, vcc, 0, v59, vcc
	v_add_co_u32_e32 v18, vcc, 0xb0000, v58
	global_load_dwordx4 v[10:13], v[10:11], off nt
	s_nop 0
	global_load_dwordx4 v[14:17], v[14:15], off nt
	v_addc_co_u32_e32 v19, vcc, 0, v59, vcc
	v_add_co_u32_e32 v22, vcc, 0xdc000, v58
	v_mov_b32_e32 v130, v62
	s_nop 0
	v_addc_co_u32_e32 v23, vcc, 0, v59, vcc
	v_add_co_u32_e32 v26, vcc, 0x108000, v58
	global_load_dwordx4 v[18:21], v[18:19], off nt
	s_nop 0
	global_load_dwordx4 v[22:25], v[22:23], off nt
	v_addc_co_u32_e32 v27, vcc, 0, v59, vcc
	v_add_co_u32_e32 v30, vcc, 0x134000, v58
	v_mov_b32_e32 v141, v64
	s_nop 0
	v_addc_co_u32_e32 v31, vcc, 0, v59, vcc
	v_add_co_u32_e32 v34, vcc, 0x160000, v58
	global_load_dwordx4 v[26:29], v[26:27], off nt
	s_nop 0
	global_load_dwordx4 v[30:33], v[30:31], off nt
	v_addc_co_u32_e32 v35, vcc, 0, v59, vcc
	v_add_co_u32_e32 v38, vcc, 0x18c000, v58
	s_nop 1
	v_addc_co_u32_e32 v39, vcc, 0, v59, vcc
	v_add_co_u32_e32 v42, vcc, 0x1b8000, v58
	global_load_dwordx4 v[34:37], v[34:35], off nt
	s_nop 0
	global_load_dwordx4 v[38:41], v[38:39], off nt
	v_addc_co_u32_e32 v43, vcc, 0, v59, vcc
	v_add_co_u32_e32 v46, vcc, 0x1e4000, v58
	s_nop 1
	v_addc_co_u32_e32 v47, vcc, 0, v59, vcc
	v_add_co_u32_e32 v50, vcc, 0x210000, v58
	global_load_dwordx4 v[42:45], v[42:43], off nt
	s_nop 0
	global_load_dwordx4 v[46:49], v[46:47], off nt
	v_addc_co_u32_e32 v51, vcc, 0, v59, vcc
	v_add_co_u32_e32 v54, vcc, 0x23c000, v58
	s_nop 1
	v_addc_co_u32_e32 v55, vcc, 0, v59, vcc
	v_add_co_u32_e32 v60, vcc, 0x268000, v58
	global_load_dwordx4 v[50:53], v[50:51], off nt
	s_nop 0
	global_load_dwordx4 v[54:57], v[54:55], off nt
	v_addc_co_u32_e32 v61, vcc, 0, v59, vcc
	v_add_co_u32_e32 v66, vcc, 0x294000, v58
	s_nop 1
	v_addc_co_u32_e32 v67, vcc, 0, v59, vcc
	global_load_dwordx4 v[58:61], v[60:61], off nt
	s_nop 0
	global_load_dwordx4 v[70:73], v[66:67], off nt

.LBB0_16:
	s_add_i32 s45, s44, s77
	s_cmpk_lt_i32 s45, 0x1600
	s_cselect_b64 s[16:17], -1, 0
	s_cmpk_gt_i32 s45, 0x15ff
	s_mul_hi_i32 s50, s45, 0x2e8ba2e9
	s_cbranch_scc1 .LBB0_19
	s_lshr_b32 s6, s50, 31
	s_ashr_i32 s7, s50, 5
	s_add_i32 s7, s7, s6
	s_mulk_i32 s7, 0xb0
	s_sub_i32 s7, s45, s7
	s_lshl_b32 s8, s7, 6
	s_lshl_b32 s18, s7, 5
	s_and_b32 s18, s18, 0xffffff80
	s_and_b32 s8, s8, 64
	s_or_b32 s8, s18, s8
	s_and_b32 s7, s7, 2
	s_add_i32 s18, s8, 0x1600
	s_cmp_eq_u32 s7, 0
	s_cselect_b32 s8, s8, s18
	s_cmp_lt_i32 s8, 0
	s_cbranch_scc1 .LBB0_19
	s_lshr_b32 s7, s50, 5
	s_add_i32 s7, s7, s6
	s_waitcnt vmcnt(23)
	v_lshl_add_u32 v64, s7, 6, v141
	v_mov_b64_e32 v[62:63], s[14:15]
	v_mad_i64_i32 v[62:63], s[6:7], v64, s5, v[62:63]
	v_lshl_add_u64 v[62:63], s[8:9], 2, v[62:63]
	s_waitcnt vmcnt(9)
	v_lshl_add_u64 v[122:123], v[132:133], 2, v[62:63]
	v_add_co_u32_e32 v66, vcc, 0x2c000, v122
	s_nop 1
	v_addc_co_u32_e32 v67, vcc, 0, v123, vcc
	v_add_co_u32_e32 v74, vcc, 0x58000, v122
	global_load_dwordx4 v[62:65], v[122:123], off nt
	s_nop 0
	global_load_dwordx4 v[66:69], v[66:67], off nt
	v_addc_co_u32_e32 v75, vcc, 0, v123, vcc
	v_add_co_u32_e32 v78, vcc, 0x84000, v122
	s_nop 1
	v_addc_co_u32_e32 v79, vcc, 0, v123, vcc
	v_add_co_u32_e32 v82, vcc, 0xb0000, v122
	global_load_dwordx4 v[74:77], v[74:75], off nt
	s_nop 0
	global_load_dwordx4 v[78:81], v[78:79], off nt
	v_addc_co_u32_e32 v83, vcc, 0, v123, vcc
	v_add_co_u32_e32 v86, vcc, 0xdc000, v122
	s_nop 1
	v_addc_co_u32_e32 v87, vcc, 0, v123, vcc
	v_add_co_u32_e32 v90, vcc, 0x108000, v122
	global_load_dwordx4 v[82:85], v[82:83], off nt
	s_nop 0
	global_load_dwordx4 v[86:89], v[86:87], off nt
	v_addc_co_u32_e32 v91, vcc, 0, v123, vcc
	v_add_co_u32_e32 v94, vcc, 0x134000, v122
	s_nop 1
	v_addc_co_u32_e32 v95, vcc, 0, v123, vcc
	v_add_co_u32_e32 v98, vcc, 0x160000, v122
	global_load_dwordx4 v[90:93], v[90:91], off nt
	s_nop 0
	global_load_dwordx4 v[94:97], v[94:95], off nt
	v_addc_co_u32_e32 v99, vcc, 0, v123, vcc
	v_add_co_u32_e32 v102, vcc, 0x18c000, v122
	s_nop 1
	v_addc_co_u32_e32 v103, vcc, 0, v123, vcc
	v_add_co_u32_e32 v106, vcc, 0x1b8000, v122
	global_load_dwordx4 v[98:101], v[98:99], off nt
	s_nop 0
	global_load_dwordx4 v[102:105], v[102:103], off nt
	v_addc_co_u32_e32 v107, vcc, 0, v123, vcc
	v_add_co_u32_e32 v110, vcc, 0x1e4000, v122
	s_nop 1
	v_addc_co_u32_e32 v111, vcc, 0, v123, vcc
	v_add_co_u32_e32 v114, vcc, 0x210000, v122
	global_load_dwordx4 v[106:109], v[106:107], off nt
	s_nop 0
	global_load_dwordx4 v[110:113], v[110:111], off nt
	v_addc_co_u32_e32 v115, vcc, 0, v123, vcc
	v_add_co_u32_e32 v118, vcc, 0x23c000, v122
	s_nop 1
	v_addc_co_u32_e32 v119, vcc, 0, v123, vcc
	v_add_co_u32_e32 v124, vcc, 0x268000, v122
	global_load_dwordx4 v[114:117], v[114:115], off nt
	s_nop 0
	global_load_dwordx4 v[118:121], v[118:119], off nt
	v_addc_co_u32_e32 v125, vcc, 0, v123, vcc
	s_waitcnt vmcnt(22)
	v_add_co_u32_e32 v126, vcc, 0x294000, v122
	s_nop 1
	v_addc_co_u32_e32 v127, vcc, 0, v123, vcc
	global_load_dwordx4 v[122:125], v[124:125], off nt
	s_nop 0
	global_load_dwordx4 v[126:129], v[126:127], off nt

.LBB0_22:
	v_mov_b32_e32 v154, 0
	v_lshl_add_u64 v[138:139], v[136:137], 0, s[18:19]
	v_mov_b32_e32 v155, 0
	s_and_saveexec_b64 s[20:21], s[6:7]
	s_cbranch_execz .LBB0_24
	global_load_dword v155, v[138:139], off nt
.LBB0_24:
	s_or_b64 exec, exec, s[20:21]
	s_waitcnt vmcnt(0)
	ds_write_b32 v130, v155
	s_and_saveexec_b64 s[20:21], s[6:7]
	s_cbranch_execz .LBB0_26
	v_add_co_u32_e32 v154, vcc, 0xb000, v138
	s_nop 1
	v_addc_co_u32_e32 v155, vcc, 0, v139, vcc
	global_load_dword v154, v[154:155], off nt
.LBB0_26:
	s_or_b64 exec, exec, s[20:21]
	s_waitcnt vmcnt(0)
	ds_write_b32 v130, v154 offset:260
	v_mov_b32_e32 v154, 0
	v_mov_b32_e32 v155, 0
	s_and_saveexec_b64 s[20:21], s[6:7]
	s_cbranch_execz .LBB0_28
	v_add_co_u32_e32 v156, vcc, 0x16000, v138
	s_nop 1
	v_addc_co_u32_e32 v157, vcc, 0, v139, vcc
	global_load_dword v155, v[156:157], off nt
.LBB0_28:
	s_or_b64 exec, exec, s[20:21]
	s_waitcnt vmcnt(0)
	ds_write_b32 v130, v155 offset:520
	s_and_saveexec_b64 s[20:21], s[6:7]
	s_cbranch_execz .LBB0_30
	v_add_co_u32_e32 v154, vcc, 0x21000, v138
	s_nop 1
	v_addc_co_u32_e32 v155, vcc, 0, v139, vcc
	global_load_dword v154, v[154:155], off nt
.LBB0_30:
	s_or_b64 exec, exec, s[20:21]
	s_waitcnt vmcnt(0)
	ds_write_b32 v130, v154 offset:780
	v_mov_b32_e32 v154, 0
	v_mov_b32_e32 v155, 0
	s_and_saveexec_b64 s[20:21], s[6:7]
	s_cbranch_execz .LBB0_32
	v_add_co_u32_e32 v156, vcc, 0x2c000, v138
	s_nop 1
	v_addc_co_u32_e32 v157, vcc, 0, v139, vcc
	global_load_dword v155, v[156:157], off nt
.LBB0_32:
	s_or_b64 exec, exec, s[20:21]
	s_waitcnt vmcnt(0)
	ds_write_b32 v130, v155 offset:1040
	s_and_saveexec_b64 s[20:21], s[6:7]
	s_cbranch_execz .LBB0_34
	v_add_co_u32_e32 v154, vcc, 0x37000, v138
	s_nop 1
	v_addc_co_u32_e32 v155, vcc, 0, v139, vcc
	global_load_dword v154, v[154:155], off nt
.LBB0_34:
	s_or_b64 exec, exec, s[20:21]
	s_waitcnt vmcnt(0)
	ds_write_b32 v130, v154 offset:1300
	v_mov_b32_e32 v154, 0
	v_mov_b32_e32 v155, 0
	s_and_saveexec_b64 s[20:21], s[6:7]
	s_cbranch_execz .LBB0_36
	v_add_co_u32_e32 v156, vcc, 0x42000, v138
	s_nop 1
	v_addc_co_u32_e32 v157, vcc, 0, v139, vcc
	global_load_dword v155, v[156:157], off nt
.LBB0_36:
	s_or_b64 exec, exec, s[20:21]
	s_waitcnt vmcnt(0)
	ds_write_b32 v130, v155 offset:1560
	s_and_saveexec_b64 s[20:21], s[6:7]
	s_cbranch_execz .LBB0_21
	v_add_co_u32_e32 v138, vcc, 0x4d000, v138
	s_nop 1
	v_addc_co_u32_e32 v139, vcc, 0, v139, vcc
	global_load_dword v154, v[138:139], off nt
	s_branch .LBB0_21

.LBB0_41:
	s_waitcnt lgkmcnt(0)
	v_add_u32_e32 v158, s44, v145
	v_ashrrev_i32_e32 v159, 31, v158
	ds_read2_b32 v[136:137], v146 offset1:65
	v_mad_i64_i32 v[158:159], s[6:7], s8, v1, v[158:159]
	s_waitcnt lgkmcnt(0)
	v_cvt_pk_bf16_f32 v136, v136, v137
	ds_read2_b32 v[138:139], v146 offset0:130 offset1:195
	v_add_u32_e32 v154, 0x400, v146
	v_lshlrev_b64 v[158:159], 7, v[158:159]
	s_waitcnt lgkmcnt(0)
	v_cvt_pk_bf16_f32 v137, v138, v139
	ds_read2_b32 v[138:139], v154 offset0:4 offset1:69
	v_lshl_add_u64 v[158:159], v[134:135], 0, v[158:159]
	s_waitcnt lgkmcnt(0)
	v_cvt_pk_bf16_f32 v138, v138, v139
	ds_read2_b32 v[156:157], v154 offset0:134 offset1:199
	s_waitcnt lgkmcnt(0)
	v_cvt_pk_bf16_f32 v139, v156, v157
	global_store_dwordx4 v[158:159], v[136:139], off
	v_add_u32_e32 v158, s44, v147
	v_ashrrev_i32_e32 v159, 31, v158
	v_mad_i64_i32 v[158:159], s[6:7], s8, v1, v[158:159]
	ds_read2_b32 v[156:157], v146 offset0:8 offset1:73
	s_waitcnt lgkmcnt(0)
	v_cvt_pk_bf16_f32 v136, v156, v157
	ds_read2_b32 v[138:139], v146 offset0:138 offset1:203
	v_lshlrev_b64 v[158:159], 7, v[158:159]
	s_waitcnt lgkmcnt(0)
	v_cvt_pk_bf16_f32 v137, v138, v139
	ds_read2_b32 v[138:139], v154 offset0:12 offset1:77
	v_lshl_add_u64 v[158:159], v[134:135], 0, v[158:159]
	s_waitcnt lgkmcnt(0)
	v_cvt_pk_bf16_f32 v138, v138, v139
	ds_read2_b32 v[156:157], v154 offset0:142 offset1:207
	s_waitcnt lgkmcnt(0)
	v_cvt_pk_bf16_f32 v139, v156, v157
	global_store_dwordx4 v[158:159], v[136:139], off
	v_add_u32_e32 v158, s44, v148
	v_ashrrev_i32_e32 v159, 31, v158
	v_mad_i64_i32 v[158:159], s[6:7], s8, v1, v[158:159]
	ds_read2_b32 v[156:157], v146 offset0:16 offset1:81
	s_waitcnt lgkmcnt(0)
	v_cvt_pk_bf16_f32 v136, v156, v157
	ds_read2_b32 v[138:139], v146 offset0:146 offset1:211
	v_lshlrev_b64 v[158:159], 7, v[158:159]
	s_waitcnt lgkmcnt(0)
	v_cvt_pk_bf16_f32 v137, v138, v139
	ds_read2_b32 v[138:139], v154 offset0:20 offset1:85
	v_lshl_add_u64 v[158:159], v[134:135], 0, v[158:159]
	s_waitcnt lgkmcnt(0)
	v_cvt_pk_bf16_f32 v138, v138, v139
	ds_read2_b32 v[156:157], v154 offset0:150 offset1:215
	s_waitcnt lgkmcnt(0)
	v_cvt_pk_bf16_f32 v139, v156, v157
	global_store_dwordx4 v[158:159], v[136:139], off
	v_add_u32_e32 v158, s44, v149
	v_ashrrev_i32_e32 v159, 31, v158
	v_mad_i64_i32 v[158:159], s[6:7], s8, v1, v[158:159]
	ds_read2_b32 v[156:157], v146 offset0:24 offset1:89
	s_waitcnt lgkmcnt(0)
	v_cvt_pk_bf16_f32 v136, v156, v157
	ds_read2_b32 v[138:139], v146 offset0:154 offset1:219
	v_lshlrev_b64 v[158:159], 7, v[158:159]
	s_waitcnt lgkmcnt(0)
	v_cvt_pk_bf16_f32 v137, v138, v139
	ds_read2_b32 v[138:139], v154 offset0:28 offset1:93
	v_lshl_add_u64 v[158:159], v[134:135], 0, v[158:159]
	s_waitcnt lgkmcnt(0)
	v_cvt_pk_bf16_f32 v138, v138, v139
	ds_read2_b32 v[156:157], v154 offset0:158 offset1:223
	s_waitcnt lgkmcnt(0)
	v_cvt_pk_bf16_f32 v139, v156, v157
	global_store_dwordx4 v[158:159], v[136:139], off
	v_add_u32_e32 v158, s44, v150
	v_ashrrev_i32_e32 v159, 31, v158
	v_mad_i64_i32 v[158:159], s[6:7], s8, v1, v[158:159]
	ds_read2_b32 v[156:157], v146 offset0:32 offset1:97
	s_waitcnt lgkmcnt(0)
	v_cvt_pk_bf16_f32 v136, v156, v157
	ds_read2_b32 v[138:139], v146 offset0:162 offset1:227
	v_lshlrev_b64 v[158:159], 7, v[158:159]
	s_waitcnt lgkmcnt(0)
	v_cvt_pk_bf16_f32 v137, v138, v139
	ds_read2_b32 v[138:139], v154 offset0:36 offset1:101
	v_lshl_add_u64 v[158:159], v[134:135], 0, v[158:159]
	s_waitcnt lgkmcnt(0)
	v_cvt_pk_bf16_f32 v138, v138, v139
	ds_read2_b32 v[156:157], v154 offset0:166 offset1:231
	s_waitcnt lgkmcnt(0)
	v_cvt_pk_bf16_f32 v139, v156, v157
	global_store_dwordx4 v[158:159], v[136:139], off
	v_add_u32_e32 v158, s44, v151
	v_ashrrev_i32_e32 v159, 31, v158
	v_mad_i64_i32 v[158:159], s[6:7], s8, v1, v[158:159]
	ds_read2_b32 v[156:157], v146 offset0:40 offset1:105
	s_waitcnt lgkmcnt(0)
	v_cvt_pk_bf16_f32 v136, v156, v157
	ds_read2_b32 v[138:139], v146 offset0:170 offset1:235
	v_lshlrev_b64 v[158:159], 7, v[158:159]
	s_waitcnt lgkmcnt(0)
	v_cvt_pk_bf16_f32 v137, v138, v139
	ds_read2_b32 v[138:139], v154 offset0:44 offset1:109
	v_lshl_add_u64 v[158:159], v[134:135], 0, v[158:159]
	s_waitcnt lgkmcnt(0)
	v_cvt_pk_bf16_f32 v138, v138, v139
	ds_read2_b32 v[156:157], v154 offset0:174 offset1:239
	s_waitcnt lgkmcnt(0)
	v_cvt_pk_bf16_f32 v139, v156, v157
	global_store_dwordx4 v[158:159], v[136:139], off
	v_add_u32_e32 v158, s44, v152
	ds_read2_b32 v[156:157], v146 offset0:48 offset1:113
	s_waitcnt lgkmcnt(0)
	v_cvt_pk_bf16_f32 v136, v156, v157
	ds_read2_b32 v[138:139], v146 offset0:178 offset1:243
	v_ashrrev_i32_e32 v159, 31, v158
	s_waitcnt lgkmcnt(0)
	v_cvt_pk_bf16_f32 v137, v138, v139
	ds_read2_b32 v[138:139], v154 offset0:52 offset1:117
	v_mad_i64_i32 v[158:159], s[6:7], s8, v1, v[158:159]
	s_waitcnt lgkmcnt(0)
	v_cvt_pk_bf16_f32 v138, v138, v139
	ds_read2_b32 v[156:157], v154 offset0:182 offset1:247
	v_lshlrev_b64 v[158:159], 7, v[158:159]
	s_waitcnt lgkmcnt(0)
	v_cvt_pk_bf16_f32 v139, v156, v157
	ds_read2_b32 v[156:157], v146 offset0:56 offset1:121
	v_lshl_add_u64 v[158:159], v[134:135], 0, v[158:159]
	global_store_dwordx4 v[158:159], v[136:139], off
	s_andn2_b64 vcc, exec, s[16:17]
	s_mov_b64 s[16:17], -1
	s_waitcnt lgkmcnt(0)
	v_cvt_pk_bf16_f32 v136, v156, v157
	v_add_u32_e32 v156, s44, v153
	v_ashrrev_i32_e32 v157, 31, v156
	v_mad_i64_i32 v[156:157], s[6:7], s8, v1, v[156:157]
	ds_read2_b32 v[138:139], v146 offset0:186 offset1:251
	v_lshlrev_b64 v[156:157], 7, v[156:157]
	s_waitcnt lgkmcnt(0)
	v_cvt_pk_bf16_f32 v137, v138, v139
	ds_read2_b32 v[138:139], v154 offset0:60 offset1:125
	v_lshl_add_u64 v[156:157], v[134:135], 0, v[156:157]
	s_waitcnt lgkmcnt(0)
	v_cvt_pk_bf16_f32 v138, v138, v139
	ds_read2_b32 v[158:159], v154 offset0:190 offset1:255
	s_waitcnt lgkmcnt(0)
	v_cvt_pk_bf16_f32 v139, v158, v159
	global_store_dwordx4 v[156:157], v[136:139], off
	s_waitcnt lgkmcnt(0)
	s_cbranch_vccnz .LBB0_15
	s_add_i32 s44, s45, s77
	s_cmpk_gt_i32 s44, 0x15ff
	s_cselect_b64 s[16:17], -1, 0
	s_and_b64 vcc, exec, s[16:17]
	s_cbranch_vccnz .LBB0_45
	s_mul_hi_i32 s6, s44, 0x2e8ba2e9
	s_lshr_b32 s7, s6, 31
	s_ashr_i32 s6, s6, 5
	s_add_i32 s6, s6, s7
	s_mul_i32 s7, s6, 0xb0
	s_sub_i32 s7, s44, s7
	s_lshl_b32 s8, s7, 6
	s_lshl_b32 s18, s7, 5
	s_and_b32 s18, s18, 0xffffff80
	s_and_b32 s8, s8, 64
	s_or_b32 s8, s18, s8
	s_and_b32 s7, s7, 2
	s_add_i32 s18, s8, 0x1600
	s_cmp_eq_u32 s7, 0
	s_cselect_b32 s8, s8, s18
	s_cmp_lt_i32 s8, 0
	s_cbranch_scc1 .LBB0_45
	s_waitcnt vmcnt(23)
	v_lshl_add_u32 v4, s6, 6, v141
	v_mov_b64_e32 v[2:3], s[14:15]
	v_mad_i64_i32 v[2:3], s[6:7], v4, s5, v[2:3]
	v_lshl_add_u64 v[2:3], s[8:9], 2, v[2:3]
	s_waitcnt vmcnt(9)
	v_lshl_add_u64 v[58:59], v[132:133], 2, v[2:3]
	v_add_co_u32_e32 v6, vcc, 0x2c000, v58
	s_nop 1
	v_addc_co_u32_e32 v7, vcc, 0, v59, vcc
	v_add_co_u32_e32 v10, vcc, 0x58000, v58
	global_load_dwordx4 v[2:5], v[58:59], off nt
	s_nop 0
	global_load_dwordx4 v[6:9], v[6:7], off nt
	v_addc_co_u32_e32 v11, vcc, 0, v59, vcc
	v_add_co_u32_e32 v14, vcc, 0x84000, v58
	s_nop 1
	v_addc_co_u32_e32 v15, vcc, 0, v59, vcc
	v_add_co_u32_e32 v18, vcc, 0xb0000, v58
	global_load_dwordx4 v[10:13], v[10:11], off nt
	s_nop 0
	global_load_dwordx4 v[14:17], v[14:15], off nt
	v_addc_co_u32_e32 v19, vcc, 0, v59, vcc
	v_add_co_u32_e32 v22, vcc, 0xdc000, v58
	s_nop 1
	v_addc_co_u32_e32 v23, vcc, 0, v59, vcc
	v_add_co_u32_e32 v26, vcc, 0x108000, v58
	global_load_dwordx4 v[18:21], v[18:19], off nt
	s_nop 0
	global_load_dwordx4 v[22:25], v[22:23], off nt
	v_addc_co_u32_e32 v27, vcc, 0, v59, vcc
	v_add_co_u32_e32 v30, vcc, 0x134000, v58
	s_nop 1
	v_addc_co_u32_e32 v31, vcc, 0, v59, vcc
	v_add_co_u32_e32 v34, vcc, 0x160000, v58
	global_load_dwordx4 v[26:29], v[26:27], off nt
	s_nop 0
	global_load_dwordx4 v[30:33], v[30:31], off nt
	v_addc_co_u32_e32 v35, vcc, 0, v59, vcc
	v_add_co_u32_e32 v38, vcc, 0x18c000, v58
	s_nop 1
	v_addc_co_u32_e32 v39, vcc, 0, v59, vcc
	v_add_co_u32_e32 v42, vcc, 0x1b8000, v58
	global_load_dwordx4 v[34:37], v[34:35], off nt
	s_nop 0
	global_load_dwordx4 v[38:41], v[38:39], off nt
	v_addc_co_u32_e32 v43, vcc, 0, v59, vcc
	v_add_co_u32_e32 v46, vcc, 0x1e4000, v58
	s_nop 1
	v_addc_co_u32_e32 v47, vcc, 0, v59, vcc
	v_add_co_u32_e32 v50, vcc, 0x210000, v58
	global_load_dwordx4 v[42:45], v[42:43], off nt
	s_nop 0
	global_load_dwordx4 v[46:49], v[46:47], off nt
	v_addc_co_u32_e32 v51, vcc, 0, v59, vcc
	v_add_co_u32_e32 v54, vcc, 0x23c000, v58
	s_nop 1
	v_addc_co_u32_e32 v55, vcc, 0, v59, vcc
	v_add_co_u32_e32 v60, vcc, 0x268000, v58
	global_load_dwordx4 v[50:53], v[50:51], off nt
	s_nop 0
	global_load_dwordx4 v[54:57], v[54:55], off nt
	v_addc_co_u32_e32 v61, vcc, 0, v59, vcc
	s_waitcnt vmcnt(22)
	v_add_co_u32_e32 v70, vcc, 0x294000, v58
	s_nop 1
	v_addc_co_u32_e32 v71, vcc, 0, v59, vcc
	global_load_dwordx4 v[58:61], v[60:61], off nt
	s_nop 0
	global_load_dwordx4 v[70:73], v[70:71], off nt

.LBB0_48:
	v_mov_b32_e32 v155, 0
	v_lshl_add_u64 v[138:139], v[136:137], 0, s[18:19]
	v_mov_b32_e32 v156, 0
	s_and_saveexec_b64 s[20:21], s[6:7]
	s_cbranch_execz .LBB0_50
	global_load_dword v156, v[138:139], off nt
.LBB0_50:
	s_or_b64 exec, exec, s[20:21]
	s_waitcnt vmcnt(0)
	ds_write_b32 v130, v156
	s_and_saveexec_b64 s[20:21], s[6:7]
	s_cbranch_execz .LBB0_52
	v_add_co_u32_e32 v156, vcc, 0xb000, v138
	s_nop 1
	v_addc_co_u32_e32 v157, vcc, 0, v139, vcc
	global_load_dword v155, v[156:157], off nt
.LBB0_52:
	s_or_b64 exec, exec, s[20:21]
	s_waitcnt vmcnt(0)
	ds_write_b32 v130, v155 offset:260
	v_mov_b32_e32 v155, 0
	v_mov_b32_e32 v156, 0
	s_and_saveexec_b64 s[20:21], s[6:7]
	s_cbranch_execz .LBB0_54
	v_add_co_u32_e32 v156, vcc, 0x16000, v138
	s_nop 1
	v_addc_co_u32_e32 v157, vcc, 0, v139, vcc
	global_load_dword v156, v[156:157], off nt
.LBB0_54:
	s_or_b64 exec, exec, s[20:21]
	s_waitcnt vmcnt(0)
	ds_write_b32 v130, v156 offset:520
	s_and_saveexec_b64 s[20:21], s[6:7]
	s_cbranch_execz .LBB0_56
	v_add_co_u32_e32 v156, vcc, 0x21000, v138
	s_nop 1
	v_addc_co_u32_e32 v157, vcc, 0, v139, vcc
	global_load_dword v155, v[156:157], off nt
.LBB0_56:
	s_or_b64 exec, exec, s[20:21]
	s_waitcnt vmcnt(0)
	ds_write_b32 v130, v155 offset:780
	v_mov_b32_e32 v155, 0
	v_mov_b32_e32 v156, 0
	s_and_saveexec_b64 s[20:21], s[6:7]
	s_cbranch_execz .LBB0_58
	v_add_co_u32_e32 v156, vcc, 0x2c000, v138
	s_nop 1
	v_addc_co_u32_e32 v157, vcc, 0, v139, vcc
	global_load_dword v156, v[156:157], off nt
.LBB0_58:
	s_or_b64 exec, exec, s[20:21]
	s_waitcnt vmcnt(0)
	ds_write_b32 v130, v156 offset:1040
	s_and_saveexec_b64 s[20:21], s[6:7]
	s_cbranch_execz .LBB0_60
	v_add_co_u32_e32 v156, vcc, 0x37000, v138
	s_nop 1
	v_addc_co_u32_e32 v157, vcc, 0, v139, vcc
	global_load_dword v155, v[156:157], off nt
.LBB0_60:
	s_or_b64 exec, exec, s[20:21]
	s_waitcnt vmcnt(0)
	ds_write_b32 v130, v155 offset:1300
	v_mov_b32_e32 v155, 0
	v_mov_b32_e32 v156, 0
	s_and_saveexec_b64 s[20:21], s[6:7]
	s_cbranch_execz .LBB0_62
	v_add_co_u32_e32 v156, vcc, 0x42000, v138
	s_nop 1
	v_addc_co_u32_e32 v157, vcc, 0, v139, vcc
	global_load_dword v156, v[156:157], off nt
.LBB0_62:
	s_or_b64 exec, exec, s[20:21]
	s_waitcnt vmcnt(0)
	ds_write_b32 v130, v156 offset:1560
	s_and_saveexec_b64 s[20:21], s[6:7]
	s_cbranch_execz .LBB0_47
	v_add_co_u32_e32 v138, vcc, 0x4d000, v138
	s_nop 1
	v_addc_co_u32_e32 v139, vcc, 0, v139, vcc
	global_load_dword v155, v[138:139], off nt
	s_branch .LBB0_47

.LBB0_70:
	s_andn2_b64 vcc, exec, s[16:17]
	s_cbranch_vccnz .LBB0_72
	s_ashr_i32 s16, s8, 5
	v_lshl_add_u32 v2, s16, 6, v64
	v_ashrrev_i32_e32 v3, 31, v2
	v_lshlrev_b64 v[2:3], 13, v[2:3]
	s_lshl_b32 s8, s18, 6
	v_lshl_add_u64 v[2:3], s[14:15], 0, v[2:3]
	v_lshl_add_u64 v[2:3], s[8:9], 2, v[2:3]
	v_lshlrev_b32_e32 v130, 2, v62
	s_waitcnt vmcnt(9)
	v_lshl_add_u64 v[58:59], v[2:3], 0, v[130:131]
	v_add_co_u32_e32 v6, vcc, s26, v58
	v_mov_b32_e32 v63, v131
	s_nop 0
	v_addc_co_u32_e32 v7, vcc, 0, v59, vcc
	v_add_co_u32_e32 v10, vcc, s27, v58
	global_load_dwordx4 v[2:5], v[58:59], off nt
	s_nop 0
	global_load_dwordx4 v[6:9], v[6:7], off nt
	v_addc_co_u32_e32 v11, vcc, 0, v59, vcc
	v_add_co_u32_e32 v14, vcc, s28, v58
	v_mov_b64_e32 v[132:133], v[62:63]
	s_nop 0
	v_addc_co_u32_e32 v15, vcc, 0, v59, vcc
	v_add_co_u32_e32 v18, vcc, s29, v58
	global_load_dwordx4 v[10:13], v[10:11], off nt
	s_nop 0
	global_load_dwordx4 v[14:17], v[14:15], off nt
	v_addc_co_u32_e32 v19, vcc, 0, v59, vcc
	v_add_co_u32_e32 v22, vcc, s33, v58
	v_mov_b32_e32 v130, v62
	s_nop 0
	v_addc_co_u32_e32 v23, vcc, 0, v59, vcc
	v_add_co_u32_e32 v26, vcc, s34, v58
	global_load_dwordx4 v[18:21], v[18:19], off nt
	s_nop 0
	global_load_dwordx4 v[22:25], v[22:23], off nt
	v_addc_co_u32_e32 v27, vcc, 0, v59, vcc
	v_add_co_u32_e32 v30, vcc, s35, v58
	v_mov_b32_e32 v141, v64
	s_nop 0
	v_addc_co_u32_e32 v31, vcc, 0, v59, vcc
	v_add_co_u32_e32 v34, vcc, s36, v58
	global_load_dwordx4 v[26:29], v[26:27], off nt
	s_nop 0
	global_load_dwordx4 v[30:33], v[30:31], off nt
	v_addc_co_u32_e32 v35, vcc, 0, v59, vcc
	v_add_co_u32_e32 v38, vcc, s37, v58
	s_nop 1
	v_addc_co_u32_e32 v39, vcc, 0, v59, vcc
	v_add_co_u32_e32 v42, vcc, s38, v58
	global_load_dwordx4 v[34:37], v[34:35], off nt
	s_nop 0
	global_load_dwordx4 v[38:41], v[38:39], off nt
	v_addc_co_u32_e32 v43, vcc, 0, v59, vcc
	v_add_co_u32_e32 v46, vcc, s24, v58
	s_nop 1
	v_addc_co_u32_e32 v47, vcc, 0, v59, vcc
	v_add_co_u32_e32 v50, vcc, s39, v58
	global_load_dwordx4 v[42:45], v[42:43], off nt
	s_nop 0
	global_load_dwordx4 v[46:49], v[46:47], off nt
	v_addc_co_u32_e32 v51, vcc, 0, v59, vcc
	v_add_co_u32_e32 v54, vcc, 0x68000, v58
	s_nop 1
	v_addc_co_u32_e32 v55, vcc, 0, v59, vcc
	v_add_co_u32_e32 v60, vcc, 0x70000, v58
	global_load_dwordx4 v[50:53], v[50:51], off nt
	s_nop 0
	global_load_dwordx4 v[54:57], v[54:55], off nt
	v_addc_co_u32_e32 v61, vcc, 0, v59, vcc
	v_add_co_u32_e32 v66, vcc, 0x78000, v58
	s_nop 1
	v_addc_co_u32_e32 v67, vcc, 0, v59, vcc
	global_load_dwordx4 v[58:61], v[60:61], off nt
	s_nop 0
	global_load_dwordx4 v[70:73], v[66:67], off nt

.LBB0_75:
	s_add_i32 s45, s44, s77
	s_cmpk_lt_i32 s45, 0xb00
	s_cselect_b64 s[16:17], -1, 0
	s_cmpk_gt_i32 s45, 0xaff
	s_cbranch_scc1 .LBB0_78
	s_ashr_i32 s6, s45, 31
	s_lshr_b32 s6, s6, 27
	s_add_i32 s6, s45, s6
	s_and_b32 s7, s6, 0xffffffe0
	s_sub_i32 s7, s45, s7
	s_cmp_lt_i32 s7, 0
	s_cbranch_scc1 .LBB0_78
	s_lshl_b32 s6, s6, 1
	s_andn2_b32 s6, s6, 63
	s_waitcnt vmcnt(23)
	v_add_u32_e32 v62, s6, v141
	v_ashrrev_i32_e32 v63, 31, v62
	v_lshlrev_b64 v[62:63], 13, v[62:63]
	s_lshl_b32 s8, s7, 6
	v_lshl_add_u64 v[62:63], s[14:15], 0, v[62:63]
	v_lshl_add_u64 v[62:63], s[8:9], 2, v[62:63]
	s_waitcnt vmcnt(9)
	v_lshl_add_u64 v[122:123], v[132:133], 2, v[62:63]
	v_add_co_u32_e32 v66, vcc, 0x8000, v122
	s_nop 1
	v_addc_co_u32_e32 v67, vcc, 0, v123, vcc
	v_add_co_u32_e32 v74, vcc, 0x10000, v122
	global_load_dwordx4 v[62:65], v[122:123], off nt
	s_nop 0
	global_load_dwordx4 v[66:69], v[66:67], off nt
	v_addc_co_u32_e32 v75, vcc, 0, v123, vcc
	v_add_co_u32_e32 v78, vcc, 0x18000, v122
	s_nop 1
	v_addc_co_u32_e32 v79, vcc, 0, v123, vcc
	v_add_co_u32_e32 v82, vcc, 0x20000, v122
	global_load_dwordx4 v[74:77], v[74:75], off nt
	s_nop 0
	global_load_dwordx4 v[78:81], v[78:79], off nt
	v_addc_co_u32_e32 v83, vcc, 0, v123, vcc
	v_add_co_u32_e32 v86, vcc, 0x28000, v122
	s_nop 1
	v_addc_co_u32_e32 v87, vcc, 0, v123, vcc
	v_add_co_u32_e32 v90, vcc, 0x30000, v122
	global_load_dwordx4 v[82:85], v[82:83], off nt
	s_nop 0
	global_load_dwordx4 v[86:89], v[86:87], off nt
	v_addc_co_u32_e32 v91, vcc, 0, v123, vcc
	v_add_co_u32_e32 v94, vcc, 0x38000, v122
	s_nop 1
	v_addc_co_u32_e32 v95, vcc, 0, v123, vcc
	v_add_co_u32_e32 v98, vcc, 0x40000, v122
	global_load_dwordx4 v[90:93], v[90:91], off nt
	s_nop 0
	global_load_dwordx4 v[94:97], v[94:95], off nt
	v_addc_co_u32_e32 v99, vcc, 0, v123, vcc
	v_add_co_u32_e32 v102, vcc, 0x48000, v122
	s_nop 1
	v_addc_co_u32_e32 v103, vcc, 0, v123, vcc
	v_add_co_u32_e32 v106, vcc, 0x50000, v122
	global_load_dwordx4 v[98:101], v[98:99], off nt
	s_nop 0
	global_load_dwordx4 v[102:105], v[102:103], off nt
	v_addc_co_u32_e32 v107, vcc, 0, v123, vcc
	v_add_co_u32_e32 v110, vcc, s24, v122
	s_nop 1
	v_addc_co_u32_e32 v111, vcc, 0, v123, vcc
	v_add_co_u32_e32 v114, vcc, 0x60000, v122
	global_load_dwordx4 v[106:109], v[106:107], off nt
	s_nop 0
	global_load_dwordx4 v[110:113], v[110:111], off nt
	v_addc_co_u32_e32 v115, vcc, 0, v123, vcc
	v_add_co_u32_e32 v118, vcc, 0x68000, v122
	s_nop 1
	v_addc_co_u32_e32 v119, vcc, 0, v123, vcc
	v_add_co_u32_e32 v124, vcc, 0x70000, v122
	global_load_dwordx4 v[114:117], v[114:115], off nt
	s_nop 0
	global_load_dwordx4 v[118:121], v[118:119], off nt
	v_addc_co_u32_e32 v125, vcc, 0, v123, vcc
	s_waitcnt vmcnt(22)
	v_add_co_u32_e32 v126, vcc, 0x78000, v122
	s_nop 1
	v_addc_co_u32_e32 v127, vcc, 0, v123, vcc
	global_load_dwordx4 v[122:125], v[124:125], off nt
	s_nop 0
	global_load_dwordx4 v[126:129], v[126:127], off nt

.LBB0_81:
	v_mov_b32_e32 v154, 0
	v_lshl_add_u64 v[138:139], v[136:137], 0, s[20:21]
	v_mov_b32_e32 v155, 0
	s_and_saveexec_b64 s[22:23], s[6:7]
	s_cbranch_execz .LBB0_83
	global_load_dword v155, v[138:139], off nt
.LBB0_83:
	s_or_b64 exec, exec, s[22:23]
	s_waitcnt vmcnt(0)
	ds_write_b32 v130, v155
	s_and_saveexec_b64 s[22:23], s[6:7]
	s_cbranch_execz .LBB0_85
	v_add_co_u32_e32 v154, vcc, 0x2000, v138
	s_nop 1
	v_addc_co_u32_e32 v155, vcc, 0, v139, vcc
	global_load_dword v154, v[154:155], off nt
.LBB0_85:
	s_or_b64 exec, exec, s[22:23]
	s_waitcnt vmcnt(0)
	ds_write_b32 v130, v154 offset:260
	v_mov_b32_e32 v154, 0
	v_mov_b32_e32 v155, 0
	s_and_saveexec_b64 s[22:23], s[6:7]
	s_cbranch_execz .LBB0_87
	v_add_co_u32_e32 v156, vcc, 0x4000, v138
	s_nop 1
	v_addc_co_u32_e32 v157, vcc, 0, v139, vcc
	global_load_dword v155, v[156:157], off nt
.LBB0_87:
	s_or_b64 exec, exec, s[22:23]
	s_waitcnt vmcnt(0)
	ds_write_b32 v130, v155 offset:520
	s_and_saveexec_b64 s[22:23], s[6:7]
	s_cbranch_execz .LBB0_89
	v_add_co_u32_e32 v154, vcc, 0x6000, v138
	s_nop 1
	v_addc_co_u32_e32 v155, vcc, 0, v139, vcc
	global_load_dword v154, v[154:155], off nt
.LBB0_89:
	s_or_b64 exec, exec, s[22:23]
	s_waitcnt vmcnt(0)
	ds_write_b32 v130, v154 offset:780
	v_mov_b32_e32 v154, 0
	v_mov_b32_e32 v155, 0
	s_and_saveexec_b64 s[22:23], s[6:7]
	s_cbranch_execz .LBB0_91
	v_add_co_u32_e32 v156, vcc, 0x8000, v138
	s_nop 1
	v_addc_co_u32_e32 v157, vcc, 0, v139, vcc
	global_load_dword v155, v[156:157], off nt
.LBB0_91:
	s_or_b64 exec, exec, s[22:23]
	s_waitcnt vmcnt(0)
	ds_write_b32 v130, v155 offset:1040
	s_and_saveexec_b64 s[22:23], s[6:7]
	s_cbranch_execz .LBB0_93
	v_add_co_u32_e32 v154, vcc, 0xa000, v138
	s_nop 1
	v_addc_co_u32_e32 v155, vcc, 0, v139, vcc
	global_load_dword v154, v[154:155], off nt
.LBB0_93:
	s_or_b64 exec, exec, s[22:23]
	s_waitcnt vmcnt(0)
	ds_write_b32 v130, v154 offset:1300
	v_mov_b32_e32 v154, 0
	v_mov_b32_e32 v155, 0
	s_and_saveexec_b64 s[22:23], s[6:7]
	s_cbranch_execz .LBB0_95
	v_add_co_u32_e32 v156, vcc, 0xc000, v138
	s_nop 1
	v_addc_co_u32_e32 v157, vcc, 0, v139, vcc
	global_load_dword v155, v[156:157], off nt
.LBB0_95:
	s_or_b64 exec, exec, s[22:23]
	s_waitcnt vmcnt(0)
	ds_write_b32 v130, v155 offset:1560
	s_and_saveexec_b64 s[22:23], s[6:7]
	s_cbranch_execz .LBB0_80
	v_add_co_u32_e32 v138, vcc, 0xe000, v138
	s_nop 1
	v_addc_co_u32_e32 v139, vcc, 0, v139, vcc
	global_load_dword v154, v[138:139], off nt
	s_branch .LBB0_80

.LBB0_100:
	s_waitcnt lgkmcnt(0)
	s_ashr_i32 s19, s18, 31
	v_add_u32_e32 v158, s8, v145
	s_lshl_b64 s[6:7], s[18:19], 11
	v_ashrrev_i32_e32 v159, 31, v158
	ds_read2_b32 v[136:137], v146 offset1:65
	v_lshl_add_u64 v[158:159], s[6:7], 0, v[158:159]
	s_waitcnt lgkmcnt(0)
	v_cvt_pk_bf16_f32 v136, v136, v137
	ds_read2_b32 v[138:139], v146 offset0:130 offset1:195
	v_add_u32_e32 v154, 0x400, v146
	v_lshlrev_b64 v[158:159], 7, v[158:159]
	s_waitcnt lgkmcnt(0)
	v_cvt_pk_bf16_f32 v137, v138, v139
	ds_read2_b32 v[138:139], v154 offset0:4 offset1:69
	v_lshl_add_u64 v[158:159], v[134:135], 0, v[158:159]
	s_waitcnt lgkmcnt(0)
	v_cvt_pk_bf16_f32 v138, v138, v139
	ds_read2_b32 v[156:157], v154 offset0:134 offset1:199
	s_waitcnt lgkmcnt(0)
	v_cvt_pk_bf16_f32 v139, v156, v157
	global_store_dwordx4 v[158:159], v[136:139], off
	v_add_u32_e32 v158, s8, v147
	v_ashrrev_i32_e32 v159, 31, v158
	v_lshl_add_u64 v[158:159], s[6:7], 0, v[158:159]
	ds_read2_b32 v[156:157], v146 offset0:8 offset1:73
	s_waitcnt lgkmcnt(0)
	v_cvt_pk_bf16_f32 v136, v156, v157
	ds_read2_b32 v[138:139], v146 offset0:138 offset1:203
	v_lshlrev_b64 v[158:159], 7, v[158:159]
	s_waitcnt lgkmcnt(0)
	v_cvt_pk_bf16_f32 v137, v138, v139
	ds_read2_b32 v[138:139], v154 offset0:12 offset1:77
	v_lshl_add_u64 v[158:159], v[134:135], 0, v[158:159]
	s_waitcnt lgkmcnt(0)
	v_cvt_pk_bf16_f32 v138, v138, v139
	ds_read2_b32 v[156:157], v154 offset0:142 offset1:207
	s_waitcnt lgkmcnt(0)
	v_cvt_pk_bf16_f32 v139, v156, v157
	global_store_dwordx4 v[158:159], v[136:139], off
	v_add_u32_e32 v158, s8, v148
	v_ashrrev_i32_e32 v159, 31, v158
	v_lshl_add_u64 v[158:159], s[6:7], 0, v[158:159]
	ds_read2_b32 v[156:157], v146 offset0:16 offset1:81
	s_waitcnt lgkmcnt(0)
	v_cvt_pk_bf16_f32 v136, v156, v157
	ds_read2_b32 v[138:139], v146 offset0:146 offset1:211
	v_lshlrev_b64 v[158:159], 7, v[158:159]
	s_waitcnt lgkmcnt(0)
	v_cvt_pk_bf16_f32 v137, v138, v139
	ds_read2_b32 v[138:139], v154 offset0:20 offset1:85
	v_lshl_add_u64 v[158:159], v[134:135], 0, v[158:159]
	s_waitcnt lgkmcnt(0)
	v_cvt_pk_bf16_f32 v138, v138, v139
	ds_read2_b32 v[156:157], v154 offset0:150 offset1:215
	s_waitcnt lgkmcnt(0)
	v_cvt_pk_bf16_f32 v139, v156, v157
	global_store_dwordx4 v[158:159], v[136:139], off
	v_add_u32_e32 v158, s8, v149
	v_ashrrev_i32_e32 v159, 31, v158
	v_lshl_add_u64 v[158:159], s[6:7], 0, v[158:159]
	ds_read2_b32 v[156:157], v146 offset0:24 offset1:89
	s_waitcnt lgkmcnt(0)
	v_cvt_pk_bf16_f32 v136, v156, v157
	ds_read2_b32 v[138:139], v146 offset0:154 offset1:219
	v_lshlrev_b64 v[158:159], 7, v[158:159]
	s_waitcnt lgkmcnt(0)
	v_cvt_pk_bf16_f32 v137, v138, v139
	ds_read2_b32 v[138:139], v154 offset0:28 offset1:93
	v_lshl_add_u64 v[158:159], v[134:135], 0, v[158:159]
	s_waitcnt lgkmcnt(0)
	v_cvt_pk_bf16_f32 v138, v138, v139
	ds_read2_b32 v[156:157], v154 offset0:158 offset1:223
	s_waitcnt lgkmcnt(0)
	v_cvt_pk_bf16_f32 v139, v156, v157
	global_store_dwordx4 v[158:159], v[136:139], off
	v_add_u32_e32 v158, s8, v150
	v_ashrrev_i32_e32 v159, 31, v158
	v_lshl_add_u64 v[158:159], s[6:7], 0, v[158:159]
	ds_read2_b32 v[156:157], v146 offset0:32 offset1:97
	s_waitcnt lgkmcnt(0)
	v_cvt_pk_bf16_f32 v136, v156, v157
	ds_read2_b32 v[138:139], v146 offset0:162 offset1:227
	v_lshlrev_b64 v[158:159], 7, v[158:159]
	s_waitcnt lgkmcnt(0)
	v_cvt_pk_bf16_f32 v137, v138, v139
	ds_read2_b32 v[138:139], v154 offset0:36 offset1:101
	v_lshl_add_u64 v[158:159], v[134:135], 0, v[158:159]
	s_waitcnt lgkmcnt(0)
	v_cvt_pk_bf16_f32 v138, v138, v139
	ds_read2_b32 v[156:157], v154 offset0:166 offset1:231
	s_waitcnt lgkmcnt(0)
	v_cvt_pk_bf16_f32 v139, v156, v157
	global_store_dwordx4 v[158:159], v[136:139], off
	v_add_u32_e32 v158, s8, v151
	v_ashrrev_i32_e32 v159, 31, v158
	v_lshl_add_u64 v[158:159], s[6:7], 0, v[158:159]
	ds_read2_b32 v[156:157], v146 offset0:40 offset1:105
	s_waitcnt lgkmcnt(0)
	v_cvt_pk_bf16_f32 v136, v156, v157
	ds_read2_b32 v[138:139], v146 offset0:170 offset1:235
	v_lshlrev_b64 v[158:159], 7, v[158:159]
	s_waitcnt lgkmcnt(0)
	v_cvt_pk_bf16_f32 v137, v138, v139
	ds_read2_b32 v[138:139], v154 offset0:44 offset1:109
	v_lshl_add_u64 v[158:159], v[134:135], 0, v[158:159]
	s_waitcnt lgkmcnt(0)
	v_cvt_pk_bf16_f32 v138, v138, v139
	ds_read2_b32 v[156:157], v154 offset0:174 offset1:239
	s_waitcnt lgkmcnt(0)
	v_cvt_pk_bf16_f32 v139, v156, v157
	global_store_dwordx4 v[158:159], v[136:139], off
	v_add_u32_e32 v158, s8, v152
	ds_read2_b32 v[156:157], v146 offset0:48 offset1:113
	s_waitcnt lgkmcnt(0)
	v_cvt_pk_bf16_f32 v136, v156, v157
	ds_read2_b32 v[138:139], v146 offset0:178 offset1:243
	v_ashrrev_i32_e32 v159, 31, v158
	s_waitcnt lgkmcnt(0)
	v_cvt_pk_bf16_f32 v137, v138, v139
	ds_read2_b32 v[138:139], v154 offset0:52 offset1:117
	v_lshl_add_u64 v[158:159], s[6:7], 0, v[158:159]
	s_waitcnt lgkmcnt(0)
	v_cvt_pk_bf16_f32 v138, v138, v139
	ds_read2_b32 v[156:157], v154 offset0:182 offset1:247
	v_lshlrev_b64 v[158:159], 7, v[158:159]
	s_waitcnt lgkmcnt(0)
	v_cvt_pk_bf16_f32 v139, v156, v157
	ds_read2_b32 v[156:157], v146 offset0:56 offset1:121
	v_lshl_add_u64 v[158:159], v[134:135], 0, v[158:159]
	global_store_dwordx4 v[158:159], v[136:139], off
	s_andn2_b64 vcc, exec, s[16:17]
	s_mov_b64 s[16:17], -1
	s_waitcnt lgkmcnt(0)
	v_cvt_pk_bf16_f32 v136, v156, v157
	v_add_u32_e32 v156, s8, v153
	v_ashrrev_i32_e32 v157, 31, v156
	v_lshl_add_u64 v[156:157], s[6:7], 0, v[156:157]
	ds_read2_b32 v[138:139], v146 offset0:186 offset1:251
	v_lshlrev_b64 v[156:157], 7, v[156:157]
	s_waitcnt lgkmcnt(0)
	v_cvt_pk_bf16_f32 v137, v138, v139
	ds_read2_b32 v[138:139], v154 offset0:60 offset1:125
	v_lshl_add_u64 v[156:157], v[134:135], 0, v[156:157]
	s_waitcnt lgkmcnt(0)
	v_cvt_pk_bf16_f32 v138, v138, v139
	ds_read2_b32 v[158:159], v154 offset0:190 offset1:255
	s_waitcnt lgkmcnt(0)
	v_cvt_pk_bf16_f32 v139, v158, v159
	global_store_dwordx4 v[156:157], v[136:139], off
	s_waitcnt lgkmcnt(0)
	s_cbranch_vccnz .LBB0_74
	s_add_i32 s44, s45, s77
	s_cmpk_gt_i32 s44, 0xaff
	s_cselect_b64 s[16:17], -1, 0
	s_and_b64 vcc, exec, s[16:17]
	s_cbranch_vccnz .LBB0_104
	s_ashr_i32 s6, s44, 31
	s_lshr_b32 s6, s6, 27
	s_add_i32 s6, s44, s6
	s_and_b32 s7, s6, 0xffffffe0
	s_sub_i32 s7, s44, s7
	s_cmp_lt_i32 s7, 0
	s_cbranch_scc1 .LBB0_104
	s_ashr_i32 s6, s6, 5
	s_waitcnt vmcnt(23)
	v_lshl_add_u32 v2, s6, 6, v141
	v_ashrrev_i32_e32 v3, 31, v2
	v_lshlrev_b64 v[2:3], 13, v[2:3]
	s_lshl_b32 s8, s7, 6
	v_lshl_add_u64 v[2:3], s[14:15], 0, v[2:3]
	v_lshl_add_u64 v[2:3], s[8:9], 2, v[2:3]
	s_waitcnt vmcnt(9)
	v_lshl_add_u64 v[58:59], v[132:133], 2, v[2:3]
	v_add_co_u32_e32 v6, vcc, 0x8000, v58
	s_nop 1
	v_addc_co_u32_e32 v7, vcc, 0, v59, vcc
	v_add_co_u32_e32 v10, vcc, 0x10000, v58
	global_load_dwordx4 v[2:5], v[58:59], off nt
	s_nop 0
	global_load_dwordx4 v[6:9], v[6:7], off nt
	v_addc_co_u32_e32 v11, vcc, 0, v59, vcc
	v_add_co_u32_e32 v14, vcc, 0x18000, v58
	s_nop 1
	v_addc_co_u32_e32 v15, vcc, 0, v59, vcc
	v_add_co_u32_e32 v18, vcc, 0x20000, v58
	global_load_dwordx4 v[10:13], v[10:11], off nt
	s_nop 0
	global_load_dwordx4 v[14:17], v[14:15], off nt
	v_addc_co_u32_e32 v19, vcc, 0, v59, vcc
	v_add_co_u32_e32 v22, vcc, 0x28000, v58
	s_nop 1
	v_addc_co_u32_e32 v23, vcc, 0, v59, vcc
	v_add_co_u32_e32 v26, vcc, 0x30000, v58
	global_load_dwordx4 v[18:21], v[18:19], off nt
	s_nop 0
	global_load_dwordx4 v[22:25], v[22:23], off nt
	v_addc_co_u32_e32 v27, vcc, 0, v59, vcc
	v_add_co_u32_e32 v30, vcc, 0x38000, v58
	s_nop 1
	v_addc_co_u32_e32 v31, vcc, 0, v59, vcc
	v_add_co_u32_e32 v34, vcc, 0x40000, v58
	global_load_dwordx4 v[26:29], v[26:27], off nt
	s_nop 0
	global_load_dwordx4 v[30:33], v[30:31], off nt
	v_addc_co_u32_e32 v35, vcc, 0, v59, vcc
	v_add_co_u32_e32 v38, vcc, 0x48000, v58
	s_nop 1
	v_addc_co_u32_e32 v39, vcc, 0, v59, vcc
	v_add_co_u32_e32 v42, vcc, 0x50000, v58
	global_load_dwordx4 v[34:37], v[34:35], off nt
	s_nop 0
	global_load_dwordx4 v[38:41], v[38:39], off nt
	v_addc_co_u32_e32 v43, vcc, 0, v59, vcc
	v_add_co_u32_e32 v46, vcc, s24, v58
	s_nop 1
	v_addc_co_u32_e32 v47, vcc, 0, v59, vcc
	v_add_co_u32_e32 v50, vcc, 0x60000, v58
	global_load_dwordx4 v[42:45], v[42:43], off nt
	s_nop 0
	global_load_dwordx4 v[46:49], v[46:47], off nt
	v_addc_co_u32_e32 v51, vcc, 0, v59, vcc
	v_add_co_u32_e32 v54, vcc, 0x68000, v58
	s_nop 1
	v_addc_co_u32_e32 v55, vcc, 0, v59, vcc
	v_add_co_u32_e32 v60, vcc, 0x70000, v58
	global_load_dwordx4 v[50:53], v[50:51], off nt
	s_nop 0
	global_load_dwordx4 v[54:57], v[54:55], off nt
	v_addc_co_u32_e32 v61, vcc, 0, v59, vcc
	s_waitcnt vmcnt(22)
	v_add_co_u32_e32 v70, vcc, 0x78000, v58
	s_nop 1
	v_addc_co_u32_e32 v71, vcc, 0, v59, vcc
	global_load_dwordx4 v[58:61], v[60:61], off nt
	s_nop 0
	global_load_dwordx4 v[70:73], v[70:71], off nt

.LBB0_107:
	v_mov_b32_e32 v155, 0
	v_lshl_add_u64 v[138:139], v[136:137], 0, s[20:21]
	v_mov_b32_e32 v156, 0
	s_and_saveexec_b64 s[22:23], s[6:7]
	s_cbranch_execz .LBB0_109
	global_load_dword v156, v[138:139], off nt
.LBB0_109:
	s_or_b64 exec, exec, s[22:23]
	s_waitcnt vmcnt(0)
	ds_write_b32 v130, v156
	s_and_saveexec_b64 s[22:23], s[6:7]
	s_cbranch_execz .LBB0_111
	v_add_co_u32_e32 v156, vcc, 0x2000, v138
	s_nop 1
	v_addc_co_u32_e32 v157, vcc, 0, v139, vcc
	global_load_dword v155, v[156:157], off nt
.LBB0_111:
	s_or_b64 exec, exec, s[22:23]
	s_waitcnt vmcnt(0)
	ds_write_b32 v130, v155 offset:260
	v_mov_b32_e32 v155, 0
	v_mov_b32_e32 v156, 0
	s_and_saveexec_b64 s[22:23], s[6:7]
	s_cbranch_execz .LBB0_113
	v_add_co_u32_e32 v156, vcc, 0x4000, v138
	s_nop 1
	v_addc_co_u32_e32 v157, vcc, 0, v139, vcc
	global_load_dword v156, v[156:157], off nt
.LBB0_113:
	s_or_b64 exec, exec, s[22:23]
	s_waitcnt vmcnt(0)
	ds_write_b32 v130, v156 offset:520
	s_and_saveexec_b64 s[22:23], s[6:7]
	s_cbranch_execz .LBB0_115
	v_add_co_u32_e32 v156, vcc, 0x6000, v138
	s_nop 1
	v_addc_co_u32_e32 v157, vcc, 0, v139, vcc
	global_load_dword v155, v[156:157], off nt
.LBB0_115:
	s_or_b64 exec, exec, s[22:23]
	s_waitcnt vmcnt(0)
	ds_write_b32 v130, v155 offset:780
	v_mov_b32_e32 v155, 0
	v_mov_b32_e32 v156, 0
	s_and_saveexec_b64 s[22:23], s[6:7]
	s_cbranch_execz .LBB0_117
	v_add_co_u32_e32 v156, vcc, 0x8000, v138
	s_nop 1
	v_addc_co_u32_e32 v157, vcc, 0, v139, vcc
	global_load_dword v156, v[156:157], off nt
.LBB0_117:
	s_or_b64 exec, exec, s[22:23]
	s_waitcnt vmcnt(0)
	ds_write_b32 v130, v156 offset:1040
	s_and_saveexec_b64 s[22:23], s[6:7]
	s_cbranch_execz .LBB0_119
	v_add_co_u32_e32 v156, vcc, 0xa000, v138
	s_nop 1
	v_addc_co_u32_e32 v157, vcc, 0, v139, vcc
	global_load_dword v155, v[156:157], off nt
.LBB0_119:
	s_or_b64 exec, exec, s[22:23]
	s_waitcnt vmcnt(0)
	ds_write_b32 v130, v155 offset:1300
	v_mov_b32_e32 v155, 0
	v_mov_b32_e32 v156, 0
	s_and_saveexec_b64 s[22:23], s[6:7]
	s_cbranch_execz .LBB0_121
	v_add_co_u32_e32 v156, vcc, 0xc000, v138
	s_nop 1
	v_addc_co_u32_e32 v157, vcc, 0, v139, vcc
	global_load_dword v156, v[156:157], off nt
.LBB0_121:
	s_or_b64 exec, exec, s[22:23]
	s_waitcnt vmcnt(0)
	ds_write_b32 v130, v156 offset:1560
	s_and_saveexec_b64 s[22:23], s[6:7]
	s_cbranch_execz .LBB0_106
	v_add_co_u32_e32 v138, vcc, 0xe000, v138
	s_nop 1
	v_addc_co_u32_e32 v139, vcc, 0, v139, vcc
	global_load_dword v155, v[138:139], off nt
	s_branch .LBB0_106

.LBB0_136:
	s_cmp_lt_i32 s8, 0
	s_cbranch_scc1 .LBB0_138
	s_waitcnt vmcnt(15)
	v_ashrrev_i32_e32 v2, 4, v133
	v_lshl_add_u32 v4, s4, 6, v2
	v_mov_b64_e32 v[2:3], s[14:15]
	v_mad_i64_i32 v[2:3], s[4:5], v4, s38, v[2:3]
	v_lshlrev_b32_e32 v4, 4, v133
	v_lshl_add_u64 v[2:3], s[8:9], 2, v[2:3]
	v_and_b32_e32 v130, 0xf0, v4
	s_waitcnt vmcnt(1)
	v_lshl_add_u64 v[58:59], v[2:3], 0, v[130:131]
	v_add_co_u32_e32 v6, vcc, 0x1a000, v58
	s_nop 1
	v_addc_co_u32_e32 v7, vcc, 0, v59, vcc
	v_add_co_u32_e32 v10, vcc, 0x34000, v58
	global_load_dwordx4 v[2:5], v[58:59], off nt
	s_nop 0
	global_load_dwordx4 v[6:9], v[6:7], off offset:384 nt
	v_addc_co_u32_e32 v11, vcc, 0, v59, vcc
	v_add_co_u32_e32 v14, vcc, 0x4e000, v58
	s_nop 1
	v_addc_co_u32_e32 v15, vcc, 0, v59, vcc
	v_add_co_u32_e32 v18, vcc, 0x68000, v58
	global_load_dwordx4 v[10:13], v[10:11], off offset:768 nt
	s_nop 0
	global_load_dwordx4 v[14:17], v[14:15], off offset:1152 nt
	v_addc_co_u32_e32 v19, vcc, 0, v59, vcc
	v_add_co_u32_e32 v22, vcc, 0x82000, v58
	s_nop 1
	v_addc_co_u32_e32 v23, vcc, 0, v59, vcc
	v_add_co_u32_e32 v26, vcc, 0x9c000, v58
	global_load_dwordx4 v[18:21], v[18:19], off offset:1536 nt
	s_nop 0
	global_load_dwordx4 v[22:25], v[22:23], off offset:1920 nt
	v_addc_co_u32_e32 v27, vcc, 0, v59, vcc
	v_add_co_u32_e32 v30, vcc, 0xb6000, v58
	s_nop 1
	v_addc_co_u32_e32 v31, vcc, 0, v59, vcc
	v_add_co_u32_e32 v34, vcc, 0xd0000, v58
	global_load_dwordx4 v[26:29], v[26:27], off offset:2304 nt
	s_nop 0
	global_load_dwordx4 v[30:33], v[30:31], off offset:2688 nt
	v_addc_co_u32_e32 v35, vcc, 0, v59, vcc
	v_add_co_u32_e32 v38, vcc, 0xea000, v58
	s_nop 1
	v_addc_co_u32_e32 v39, vcc, 0, v59, vcc
	v_add_co_u32_e32 v42, vcc, 0x104000, v58
	global_load_dwordx4 v[34:37], v[34:35], off offset:3072 nt
	s_nop 0
	global_load_dwordx4 v[38:41], v[38:39], off offset:3456 nt
	v_addc_co_u32_e32 v43, vcc, 0, v59, vcc
	v_add_co_u32_e32 v46, vcc, 0x11f000, v58
	s_nop 1
	v_addc_co_u32_e32 v47, vcc, 0, v59, vcc
	v_add_co_u32_e32 v50, vcc, 0x139000, v58
	global_load_dwordx4 v[42:45], v[42:43], off offset:3840 nt
	s_nop 0
	global_load_dwordx4 v[46:49], v[46:47], off offset:128 nt
	v_addc_co_u32_e32 v51, vcc, 0, v59, vcc
	v_add_co_u32_e32 v54, vcc, 0x153000, v58
	s_nop 1
	v_addc_co_u32_e32 v55, vcc, 0, v59, vcc
	v_add_co_u32_e32 v60, vcc, 0x16d000, v58
	global_load_dwordx4 v[50:53], v[50:51], off offset:512 nt
	s_nop 0
	global_load_dwordx4 v[54:57], v[54:55], off offset:896 nt
	v_addc_co_u32_e32 v61, vcc, 0, v59, vcc
	s_waitcnt vmcnt(14)
	v_add_co_u32_e32 v62, vcc, 0x187000, v58
	s_nop 1
	v_addc_co_u32_e32 v63, vcc, 0, v59, vcc
	global_load_dwordx4 v[58:61], v[60:61], off offset:1280 nt
	s_nop 0
	global_load_dwordx4 v[62:65], v[62:63], off offset:1664 nt

.LBB0_150:
	s_cmp_lt_i32 s8, 0
	s_cbranch_scc1 .LBB0_152
	s_lshr_b32 s6, s5, 5
	s_add_i32 s6, s6, s18
	s_waitcnt vmcnt(23)
	v_lshl_add_u32 v68, s6, 6, v140
	v_mov_b64_e32 v[66:67], s[14:15]
	v_mad_i64_i32 v[66:67], s[6:7], v68, s38, v[66:67]
	v_lshl_add_u64 v[66:67], s[8:9], 2, v[66:67]
	v_lshlrev_b32_e32 v130, 2, v132
	s_waitcnt vmcnt(9)
	v_lshl_add_u64 v[122:123], v[66:67], 0, v[130:131]
	s_waitcnt vmcnt(8)
	v_add_co_u32_e32 v70, vcc, 0x1a000, v122
	s_nop 1
	v_addc_co_u32_e32 v71, vcc, 0, v123, vcc
	v_add_co_u32_e32 v74, vcc, 0x34000, v122
	global_load_dwordx4 v[66:69], v[122:123], off nt
	s_nop 0
	global_load_dwordx4 v[70:73], v[70:71], off offset:384 nt
	v_addc_co_u32_e32 v75, vcc, 0, v123, vcc
	v_add_co_u32_e32 v78, vcc, 0x4e000, v122
	s_nop 1
	v_addc_co_u32_e32 v79, vcc, 0, v123, vcc
	v_add_co_u32_e32 v82, vcc, 0x68000, v122
	global_load_dwordx4 v[74:77], v[74:75], off offset:768 nt
	s_nop 0
	global_load_dwordx4 v[78:81], v[78:79], off offset:1152 nt
	v_addc_co_u32_e32 v83, vcc, 0, v123, vcc
	v_add_co_u32_e32 v86, vcc, 0x82000, v122
	s_nop 1
	v_addc_co_u32_e32 v87, vcc, 0, v123, vcc
	v_add_co_u32_e32 v90, vcc, 0x9c000, v122
	global_load_dwordx4 v[82:85], v[82:83], off offset:1536 nt
	s_nop 0
	global_load_dwordx4 v[86:89], v[86:87], off offset:1920 nt
	v_addc_co_u32_e32 v91, vcc, 0, v123, vcc
	v_add_co_u32_e32 v94, vcc, 0xb6000, v122
	s_nop 1
	v_addc_co_u32_e32 v95, vcc, 0, v123, vcc
	v_add_co_u32_e32 v98, vcc, 0xd0000, v122
	global_load_dwordx4 v[90:93], v[90:91], off offset:2304 nt
	s_nop 0
	global_load_dwordx4 v[94:97], v[94:95], off offset:2688 nt
	v_addc_co_u32_e32 v99, vcc, 0, v123, vcc
	v_add_co_u32_e32 v102, vcc, 0xea000, v122
	s_nop 1
	v_addc_co_u32_e32 v103, vcc, 0, v123, vcc
	v_add_co_u32_e32 v106, vcc, 0x104000, v122
	global_load_dwordx4 v[98:101], v[98:99], off offset:3072 nt
	s_nop 0
	global_load_dwordx4 v[102:105], v[102:103], off offset:3456 nt
	v_addc_co_u32_e32 v107, vcc, 0, v123, vcc
	v_add_co_u32_e32 v110, vcc, 0x11f000, v122
	s_nop 1
	v_addc_co_u32_e32 v111, vcc, 0, v123, vcc
	v_add_co_u32_e32 v114, vcc, 0x139000, v122
	global_load_dwordx4 v[106:109], v[106:107], off offset:3840 nt
	s_nop 0
	global_load_dwordx4 v[110:113], v[110:111], off offset:128 nt
	v_addc_co_u32_e32 v115, vcc, 0, v123, vcc
	v_add_co_u32_e32 v118, vcc, 0x153000, v122
	s_nop 1
	v_addc_co_u32_e32 v119, vcc, 0, v123, vcc
	v_add_co_u32_e32 v124, vcc, 0x16d000, v122
	global_load_dwordx4 v[114:117], v[114:115], off offset:512 nt
	s_nop 0
	global_load_dwordx4 v[118:121], v[118:119], off offset:896 nt
	v_addc_co_u32_e32 v125, vcc, 0, v123, vcc
	v_add_co_u32_e32 v126, vcc, 0x187000, v122
	s_nop 1
	v_addc_co_u32_e32 v127, vcc, 0, v123, vcc
	global_load_dwordx4 v[122:125], v[124:125], off offset:1280 nt
	s_nop 0
	global_load_dwordx4 v[126:129], v[126:127], off offset:1664 nt

.LBB0_175:
	v_mov_b32_e32 v153, 0
	v_lshl_add_u64 v[138:139], v[136:137], 0, s[18:19]
	v_mov_b32_e32 v154, 0
	s_and_saveexec_b64 s[20:21], s[6:7]
	s_cbranch_execz .LBB0_177
	global_load_dword v154, v[138:139], off nt
.LBB0_177:
	s_or_b64 exec, exec, s[20:21]
	s_waitcnt vmcnt(0)
	ds_write_b32 v130, v154
	s_and_saveexec_b64 s[20:21], s[6:7]
	s_cbranch_execz .LBB0_179
	v_add_co_u32_e32 v154, vcc, 0x6000, v138
	s_nop 1
	v_addc_co_u32_e32 v155, vcc, 0, v139, vcc
	global_load_dword v153, v[154:155], off offset:2144 nt
.LBB0_179:
	s_or_b64 exec, exec, s[20:21]
	s_waitcnt vmcnt(0)
	ds_write_b32 v130, v153 offset:260
	v_mov_b32_e32 v153, 0
	v_mov_b32_e32 v154, 0
	s_and_saveexec_b64 s[20:21], s[6:7]
	s_cbranch_execz .LBB0_181
	v_add_co_u32_e32 v154, vcc, 0xd000, v138
	s_nop 1
	v_addc_co_u32_e32 v155, vcc, 0, v139, vcc
	global_load_dword v154, v[154:155], off offset:192 nt
.LBB0_181:
	s_or_b64 exec, exec, s[20:21]
	s_waitcnt vmcnt(0)
	ds_write_b32 v130, v154 offset:520
	s_and_saveexec_b64 s[20:21], s[6:7]
	s_cbranch_execz .LBB0_183
	v_add_co_u32_e32 v154, vcc, 0x13000, v138
	s_nop 1
	v_addc_co_u32_e32 v155, vcc, 0, v139, vcc
	global_load_dword v153, v[154:155], off offset:2336 nt
.LBB0_183:
	s_or_b64 exec, exec, s[20:21]
	s_waitcnt vmcnt(0)
	ds_write_b32 v130, v153 offset:780
	v_mov_b32_e32 v153, 0
	v_mov_b32_e32 v154, 0
	s_and_saveexec_b64 s[20:21], s[6:7]
	s_cbranch_execz .LBB0_185
	v_add_co_u32_e32 v154, vcc, 0x1a000, v138
	s_nop 1
	v_addc_co_u32_e32 v155, vcc, 0, v139, vcc
	global_load_dword v154, v[154:155], off offset:384 nt
.LBB0_185:
	s_or_b64 exec, exec, s[20:21]
	s_waitcnt vmcnt(0)
	ds_write_b32 v130, v154 offset:1040
	s_and_saveexec_b64 s[20:21], s[6:7]
	s_cbranch_execz .LBB0_187
	v_add_co_u32_e32 v154, vcc, 0x20000, v138
	s_nop 1
	v_addc_co_u32_e32 v155, vcc, 0, v139, vcc
	global_load_dword v153, v[154:155], off offset:2528 nt
.LBB0_187:
	s_or_b64 exec, exec, s[20:21]
	s_waitcnt vmcnt(0)
	ds_write_b32 v130, v153 offset:1300
	v_mov_b32_e32 v153, 0
	v_mov_b32_e32 v154, 0
	s_and_saveexec_b64 s[20:21], s[6:7]
	s_cbranch_execz .LBB0_189
	v_add_co_u32_e32 v154, vcc, 0x27000, v138
	s_nop 1
	v_addc_co_u32_e32 v155, vcc, 0, v139, vcc
	global_load_dword v154, v[154:155], off offset:576 nt
.LBB0_189:
	s_or_b64 exec, exec, s[20:21]
	s_waitcnt vmcnt(0)
	ds_write_b32 v130, v154 offset:1560
	s_and_saveexec_b64 s[20:21], s[6:7]
	s_cbranch_execz .LBB0_174
	v_add_co_u32_e32 v138, vcc, 0x2d000, v138
	s_nop 1
	v_addc_co_u32_e32 v139, vcc, 0, v139, vcc
	global_load_dword v153, v[138:139], off offset:2720 nt
	s_branch .LBB0_174

.LBB0_203:
	s_cmp_lt_i32 s8, 0
	s_cbranch_scc1 .LBB0_205
	s_waitcnt vmcnt(23)
	v_lshl_add_u32 v4, s18, 6, v140
	v_mov_b64_e32 v[2:3], s[14:15]
	v_mad_i64_i32 v[2:3], s[6:7], v4, s38, v[2:3]
	v_lshl_add_u64 v[2:3], s[8:9], 2, v[2:3]
	v_lshlrev_b32_e32 v130, 2, v132
	s_waitcnt vmcnt(9)
	v_lshl_add_u64 v[58:59], v[2:3], 0, v[130:131]
	v_add_co_u32_e32 v6, vcc, 0x1a000, v58
	s_nop 1
	v_addc_co_u32_e32 v7, vcc, 0, v59, vcc
	v_add_co_u32_e32 v10, vcc, 0x34000, v58
	global_load_dwordx4 v[2:5], v[58:59], off nt
	s_nop 0
	global_load_dwordx4 v[6:9], v[6:7], off offset:384 nt
	v_addc_co_u32_e32 v11, vcc, 0, v59, vcc
	v_add_co_u32_e32 v14, vcc, 0x4e000, v58
	s_nop 1
	v_addc_co_u32_e32 v15, vcc, 0, v59, vcc
	v_add_co_u32_e32 v18, vcc, 0x68000, v58
	global_load_dwordx4 v[10:13], v[10:11], off offset:768 nt
	s_nop 0
	global_load_dwordx4 v[14:17], v[14:15], off offset:1152 nt
	v_addc_co_u32_e32 v19, vcc, 0, v59, vcc
	v_add_co_u32_e32 v22, vcc, 0x82000, v58
	s_nop 1
	v_addc_co_u32_e32 v23, vcc, 0, v59, vcc
	v_add_co_u32_e32 v26, vcc, 0x9c000, v58
	global_load_dwordx4 v[18:21], v[18:19], off offset:1536 nt
	s_nop 0
	global_load_dwordx4 v[22:25], v[22:23], off offset:1920 nt
	v_addc_co_u32_e32 v27, vcc, 0, v59, vcc
	v_add_co_u32_e32 v30, vcc, 0xb6000, v58
	s_nop 1
	v_addc_co_u32_e32 v31, vcc, 0, v59, vcc
	v_add_co_u32_e32 v34, vcc, 0xd0000, v58
	global_load_dwordx4 v[26:29], v[26:27], off offset:2304 nt
	s_nop 0
	global_load_dwordx4 v[30:33], v[30:31], off offset:2688 nt
	v_addc_co_u32_e32 v35, vcc, 0, v59, vcc
	v_add_co_u32_e32 v38, vcc, 0xea000, v58
	s_nop 1
	v_addc_co_u32_e32 v39, vcc, 0, v59, vcc
	v_add_co_u32_e32 v42, vcc, 0x104000, v58
	global_load_dwordx4 v[34:37], v[34:35], off offset:3072 nt
	s_nop 0
	global_load_dwordx4 v[38:41], v[38:39], off offset:3456 nt
	v_addc_co_u32_e32 v43, vcc, 0, v59, vcc
	v_add_co_u32_e32 v46, vcc, 0x11f000, v58
	s_nop 1
	v_addc_co_u32_e32 v47, vcc, 0, v59, vcc
	v_add_co_u32_e32 v50, vcc, 0x139000, v58
	global_load_dwordx4 v[42:45], v[42:43], off offset:3840 nt
	s_nop 0
	global_load_dwordx4 v[46:49], v[46:47], off offset:128 nt
	v_addc_co_u32_e32 v51, vcc, 0, v59, vcc
	v_add_co_u32_e32 v54, vcc, 0x153000, v58
	s_nop 1
	v_addc_co_u32_e32 v55, vcc, 0, v59, vcc
	v_add_co_u32_e32 v60, vcc, 0x16d000, v58
	global_load_dwordx4 v[50:53], v[50:51], off offset:512 nt
	s_nop 0
	global_load_dwordx4 v[54:57], v[54:55], off offset:896 nt
	v_addc_co_u32_e32 v61, vcc, 0, v59, vcc
	s_waitcnt vmcnt(22)
	v_add_co_u32_e32 v62, vcc, 0x187000, v58
	s_nop 1
	v_addc_co_u32_e32 v63, vcc, 0, v59, vcc
	global_load_dwordx4 v[58:61], v[60:61], off offset:1280 nt
	s_nop 0
	global_load_dwordx4 v[62:65], v[62:63], off offset:1664 nt

.LBB0_230:
	s_or_b64 exec, exec, s[20:21]
	s_waitcnt vmcnt(0)
	ds_write_b32 v130, v155
	s_and_saveexec_b64 s[20:21], s[6:7]
	s_cbranch_execz .LBB0_232
	v_add_co_u32_e32 v154, vcc, 0x6000, v138
	s_nop 1
	v_addc_co_u32_e32 v155, vcc, 0, v139, vcc
	global_load_dword v154, v[154:155], off offset:2144 nt
.LBB0_232:
	s_or_b64 exec, exec, s[20:21]
	s_waitcnt vmcnt(0)
	ds_write_b32 v130, v154 offset:260
	v_mov_b32_e32 v154, 0
	v_mov_b32_e32 v155, 0
	s_and_saveexec_b64 s[20:21], s[6:7]
	s_cbranch_execz .LBB0_234
	v_add_co_u32_e32 v156, vcc, 0xd000, v138
	s_nop 1
	v_addc_co_u32_e32 v157, vcc, 0, v139, vcc
	global_load_dword v155, v[156:157], off offset:192 nt
.LBB0_234:
	s_or_b64 exec, exec, s[20:21]
	s_waitcnt vmcnt(0)
	ds_write_b32 v130, v155 offset:520
	s_and_saveexec_b64 s[20:21], s[6:7]
	s_cbranch_execz .LBB0_236
	v_add_co_u32_e32 v154, vcc, 0x13000, v138
	s_nop 1
	v_addc_co_u32_e32 v155, vcc, 0, v139, vcc
	global_load_dword v154, v[154:155], off offset:2336 nt
.LBB0_236:
	s_or_b64 exec, exec, s[20:21]
	s_waitcnt vmcnt(0)
	ds_write_b32 v130, v154 offset:780
	v_mov_b32_e32 v154, 0
	v_mov_b32_e32 v155, 0
	s_and_saveexec_b64 s[20:21], s[6:7]
	s_cbranch_execz .LBB0_238
	v_add_co_u32_e32 v156, vcc, 0x1a000, v138
	s_nop 1
	v_addc_co_u32_e32 v157, vcc, 0, v139, vcc
	global_load_dword v155, v[156:157], off offset:384 nt
.LBB0_238:
	s_or_b64 exec, exec, s[20:21]
	s_waitcnt vmcnt(0)
	ds_write_b32 v130, v155 offset:1040
	s_and_saveexec_b64 s[20:21], s[6:7]
	s_cbranch_execz .LBB0_240
	v_add_co_u32_e32 v154, vcc, 0x20000, v138
	s_nop 1
	v_addc_co_u32_e32 v155, vcc, 0, v139, vcc
	global_load_dword v154, v[154:155], off offset:2528 nt
.LBB0_240:
	s_or_b64 exec, exec, s[20:21]
	s_waitcnt vmcnt(0)
	ds_write_b32 v130, v154 offset:1300
	v_mov_b32_e32 v154, 0
	v_mov_b32_e32 v155, 0
	s_and_saveexec_b64 s[20:21], s[6:7]
	s_cbranch_execz .LBB0_242
	v_add_co_u32_e32 v156, vcc, 0x27000, v138
	s_nop 1
	v_addc_co_u32_e32 v157, vcc, 0, v139, vcc
	global_load_dword v155, v[156:157], off offset:576 nt
.LBB0_242:
	s_or_b64 exec, exec, s[20:21]
	s_waitcnt vmcnt(0)
	ds_write_b32 v130, v155 offset:1560
	s_and_saveexec_b64 s[20:21], s[6:7]
	s_cbranch_execz .LBB0_227
	v_add_co_u32_e32 v138, vcc, 0x2d000, v138
	s_nop 1
	v_addc_co_u32_e32 v139, vcc, 0, v139, vcc
	global_load_dword v154, v[138:139], off offset:2720 nt
	s_branch .LBB0_227

.LBB0_252:
	s_andn2_b64 vcc, exec, s[16:17]
	s_cbranch_vccnz .LBB0_254
	s_ashr_i32 s2, s2, 5
	v_lshl_add_u32 v2, s2, 6, v60
	v_ashrrev_i32_e32 v3, 31, v2
	v_lshlrev_b64 v[2:3], 13, v[2:3]
	s_lshl_b32 s8, s4, 6
	v_lshl_add_u64 v[2:3], s[20:21], 0, v[2:3]
	v_lshl_add_u64 v[2:3], s[8:9], 2, v[2:3]
	v_lshlrev_b32_e32 v130, 2, v58
	s_waitcnt vmcnt(0)
	v_lshl_add_u64 v[62:63], v[2:3], 0, v[130:131]
	v_add_co_u32_e32 v6, vcc, s57, v62
	v_mov_b32_e32 v59, v131
	s_nop 0
	v_addc_co_u32_e32 v7, vcc, 0, v63, vcc
	v_add_co_u32_e32 v10, vcc, s58, v62
	global_load_dwordx4 v[2:5], v[62:63], off nt
	s_nop 0
	global_load_dwordx4 v[6:9], v[6:7], off nt
	v_addc_co_u32_e32 v11, vcc, 0, v63, vcc
	v_add_co_u32_e32 v14, vcc, s59, v62
	v_mov_b64_e32 v[132:133], v[58:59]
	s_nop 0
	v_addc_co_u32_e32 v15, vcc, 0, v63, vcc
	v_add_co_u32_e32 v18, vcc, s45, v62
	global_load_dwordx4 v[10:13], v[10:11], off nt
	s_nop 0
	global_load_dwordx4 v[14:17], v[14:15], off nt
	v_addc_co_u32_e32 v19, vcc, 0, v63, vcc
	v_add_co_u32_e32 v22, vcc, s60, v62
	v_mov_b32_e32 v130, v58
	s_nop 0
	v_addc_co_u32_e32 v23, vcc, 0, v63, vcc
	v_add_co_u32_e32 v26, vcc, s61, v62
	global_load_dwordx4 v[18:21], v[18:19], off nt
	s_nop 0
	global_load_dwordx4 v[22:25], v[22:23], off nt
	v_addc_co_u32_e32 v27, vcc, 0, v63, vcc
	v_add_co_u32_e32 v30, vcc, s62, v62
	v_mov_b32_e32 v141, v60
	s_nop 0
	v_addc_co_u32_e32 v31, vcc, 0, v63, vcc
	v_add_co_u32_e32 v34, vcc, s63, v62
	global_load_dwordx4 v[26:29], v[26:27], off nt
	s_nop 0
	global_load_dwordx4 v[30:33], v[30:31], off nt
	v_addc_co_u32_e32 v35, vcc, 0, v63, vcc
	v_add_co_u32_e32 v38, vcc, s66, v62
	s_nop 1
	v_addc_co_u32_e32 v39, vcc, 0, v63, vcc
	v_add_co_u32_e32 v42, vcc, 0x50000, v62
	global_load_dwordx4 v[34:37], v[34:35], off nt
	s_nop 0
	global_load_dwordx4 v[38:41], v[38:39], off nt
	v_addc_co_u32_e32 v43, vcc, 0, v63, vcc
	v_add_co_u32_e32 v46, vcc, 0x58000, v62
	s_nop 1
	v_addc_co_u32_e32 v47, vcc, 0, v63, vcc
	v_add_co_u32_e32 v50, vcc, 0x60000, v62
	global_load_dwordx4 v[42:45], v[42:43], off nt
	s_nop 0
	global_load_dwordx4 v[46:49], v[46:47], off nt
	v_addc_co_u32_e32 v51, vcc, 0, v63, vcc
	v_add_co_u32_e32 v54, vcc, 0x68000, v62
	s_nop 1
	v_addc_co_u32_e32 v55, vcc, 0, v63, vcc
	v_add_co_u32_e32 v64, vcc, 0x70000, v62
	global_load_dwordx4 v[50:53], v[50:51], off nt
	s_nop 0
	global_load_dwordx4 v[54:57], v[54:55], off nt
	v_addc_co_u32_e32 v65, vcc, 0, v63, vcc
	v_add_co_u32_e32 v66, vcc, 0x78000, v62
	s_nop 1
	v_addc_co_u32_e32 v67, vcc, 0, v63, vcc
	global_load_dwordx4 v[62:65], v[64:65], off nt
	s_nop 0
	global_load_dwordx4 v[70:73], v[66:67], off nt

.LBB0_257:
	s_add_i32 s33, s5, s77
	s_cmpk_lt_i32 s33, 0x400
	s_cselect_b64 s[22:23], -1, 0
	s_cmpk_gt_i32 s33, 0x3ff
	s_cbranch_scc1 .LBB0_260
	s_ashr_i32 s6, s33, 31
	s_lshr_b32 s6, s6, 27
	s_add_i32 s6, s33, s6
	s_and_b32 s7, s6, 0xffffffe0
	s_sub_i32 s7, s33, s7
	s_cmp_lt_i32 s7, 0
	s_cbranch_scc1 .LBB0_260
	s_lshl_b32 s6, s6, 1
	s_andn2_b32 s6, s6, 63
	s_waitcnt vmcnt(23)
	v_add_u32_e32 v58, s6, v141
	v_ashrrev_i32_e32 v59, 31, v58
	v_lshlrev_b64 v[58:59], 13, v[58:59]
	s_lshl_b32 s8, s7, 6
	v_lshl_add_u64 v[58:59], s[20:21], 0, v[58:59]
	v_lshl_add_u64 v[58:59], s[8:9], 2, v[58:59]
	s_waitcnt vmcnt(9)
	v_lshl_add_u64 v[122:123], v[132:133], 2, v[58:59]
	v_add_co_u32_e32 v66, vcc, 0x8000, v122
	s_nop 1
	v_addc_co_u32_e32 v67, vcc, 0, v123, vcc
	v_add_co_u32_e32 v74, vcc, 0x10000, v122
	global_load_dwordx4 v[58:61], v[122:123], off nt
	s_nop 0
	global_load_dwordx4 v[66:69], v[66:67], off nt
	v_addc_co_u32_e32 v75, vcc, 0, v123, vcc
	v_add_co_u32_e32 v78, vcc, 0x18000, v122
	s_nop 1
	v_addc_co_u32_e32 v79, vcc, 0, v123, vcc
	v_add_co_u32_e32 v82, vcc, s45, v122
	global_load_dwordx4 v[74:77], v[74:75], off nt
	s_nop 0
	global_load_dwordx4 v[78:81], v[78:79], off nt
	v_addc_co_u32_e32 v83, vcc, 0, v123, vcc
	v_add_co_u32_e32 v86, vcc, 0x28000, v122
	s_nop 1
	v_addc_co_u32_e32 v87, vcc, 0, v123, vcc
	v_add_co_u32_e32 v90, vcc, 0x30000, v122
	global_load_dwordx4 v[82:85], v[82:83], off nt
	s_nop 0
	global_load_dwordx4 v[86:89], v[86:87], off nt
	v_addc_co_u32_e32 v91, vcc, 0, v123, vcc
	v_add_co_u32_e32 v94, vcc, 0x38000, v122
	s_nop 1
	v_addc_co_u32_e32 v95, vcc, 0, v123, vcc
	v_add_co_u32_e32 v98, vcc, 0x40000, v122
	global_load_dwordx4 v[90:93], v[90:91], off nt
	s_nop 0
	global_load_dwordx4 v[94:97], v[94:95], off nt
	v_addc_co_u32_e32 v99, vcc, 0, v123, vcc
	v_add_co_u32_e32 v102, vcc, 0x48000, v122
	s_nop 1
	v_addc_co_u32_e32 v103, vcc, 0, v123, vcc
	v_add_co_u32_e32 v106, vcc, 0x50000, v122
	global_load_dwordx4 v[98:101], v[98:99], off nt
	s_nop 0
	global_load_dwordx4 v[102:105], v[102:103], off nt
	v_addc_co_u32_e32 v107, vcc, 0, v123, vcc
	v_add_co_u32_e32 v110, vcc, 0x58000, v122
	s_nop 1
	v_addc_co_u32_e32 v111, vcc, 0, v123, vcc
	v_add_co_u32_e32 v114, vcc, 0x60000, v122
	global_load_dwordx4 v[106:109], v[106:107], off nt
	s_nop 0
	global_load_dwordx4 v[110:113], v[110:111], off nt
	v_addc_co_u32_e32 v115, vcc, 0, v123, vcc
	v_add_co_u32_e32 v118, vcc, 0x68000, v122
	s_nop 1
	v_addc_co_u32_e32 v119, vcc, 0, v123, vcc
	v_add_co_u32_e32 v124, vcc, 0x70000, v122
	global_load_dwordx4 v[114:117], v[114:115], off nt
	s_nop 0
	global_load_dwordx4 v[118:121], v[118:119], off nt
	v_addc_co_u32_e32 v125, vcc, 0, v123, vcc
	s_waitcnt vmcnt(22)
	v_add_co_u32_e32 v126, vcc, 0x78000, v122
	s_nop 1
	v_addc_co_u32_e32 v127, vcc, 0, v123, vcc
	global_load_dwordx4 v[122:125], v[124:125], off nt
	s_nop 0
	global_load_dwordx4 v[126:129], v[126:127], off nt

.LBB0_263:
	v_mov_b32_e32 v154, 0
	v_lshl_add_u64 v[138:139], v[136:137], 0, s[26:27]
	v_mov_b32_e32 v155, 0
	s_and_saveexec_b64 s[28:29], s[6:7]
	s_cbranch_execz .LBB0_265
	global_load_dword v155, v[138:139], off nt
.LBB0_265:
	s_or_b64 exec, exec, s[28:29]
	s_waitcnt vmcnt(0)
	ds_write_b32 v130, v155
	s_and_saveexec_b64 s[28:29], s[6:7]
	s_cbranch_execz .LBB0_267
	v_add_co_u32_e32 v154, vcc, 0x2000, v138
	s_nop 1
	v_addc_co_u32_e32 v155, vcc, 0, v139, vcc
	global_load_dword v154, v[154:155], off nt
.LBB0_267:
	s_or_b64 exec, exec, s[28:29]
	s_waitcnt vmcnt(0)
	ds_write_b32 v130, v154 offset:260
	v_mov_b32_e32 v154, 0
	v_mov_b32_e32 v155, 0
	s_and_saveexec_b64 s[28:29], s[6:7]
	s_cbranch_execz .LBB0_269
	v_add_co_u32_e32 v156, vcc, 0x4000, v138
	s_nop 1
	v_addc_co_u32_e32 v157, vcc, 0, v139, vcc
	global_load_dword v155, v[156:157], off nt
.LBB0_269:
	s_or_b64 exec, exec, s[28:29]
	s_waitcnt vmcnt(0)
	ds_write_b32 v130, v155 offset:520
	s_and_saveexec_b64 s[28:29], s[6:7]
	s_cbranch_execz .LBB0_271
	v_add_co_u32_e32 v154, vcc, 0x6000, v138
	s_nop 1
	v_addc_co_u32_e32 v155, vcc, 0, v139, vcc
	global_load_dword v154, v[154:155], off nt
.LBB0_271:
	s_or_b64 exec, exec, s[28:29]
	s_waitcnt vmcnt(0)
	ds_write_b32 v130, v154 offset:780
	v_mov_b32_e32 v154, 0
	v_mov_b32_e32 v155, 0
	s_and_saveexec_b64 s[28:29], s[6:7]
	s_cbranch_execz .LBB0_273
	v_add_co_u32_e32 v156, vcc, 0x8000, v138
	s_nop 1
	v_addc_co_u32_e32 v157, vcc, 0, v139, vcc
	global_load_dword v155, v[156:157], off nt
.LBB0_273:
	s_or_b64 exec, exec, s[28:29]
	s_waitcnt vmcnt(0)
	ds_write_b32 v130, v155 offset:1040
	s_and_saveexec_b64 s[28:29], s[6:7]
	s_cbranch_execz .LBB0_275
	v_add_co_u32_e32 v154, vcc, 0xa000, v138
	s_nop 1
	v_addc_co_u32_e32 v155, vcc, 0, v139, vcc
	global_load_dword v154, v[154:155], off nt
.LBB0_275:
	s_or_b64 exec, exec, s[28:29]
	s_waitcnt vmcnt(0)
	ds_write_b32 v130, v154 offset:1300
	v_mov_b32_e32 v154, 0
	v_mov_b32_e32 v155, 0
	s_and_saveexec_b64 s[28:29], s[6:7]
	s_cbranch_execz .LBB0_277
	v_add_co_u32_e32 v156, vcc, 0xc000, v138
	s_nop 1
	v_addc_co_u32_e32 v157, vcc, 0, v139, vcc
	global_load_dword v155, v[156:157], off nt
.LBB0_277:
	s_or_b64 exec, exec, s[28:29]
	s_waitcnt vmcnt(0)
	ds_write_b32 v130, v155 offset:1560
	s_and_saveexec_b64 s[28:29], s[6:7]
	s_cbranch_execz .LBB0_262
	v_add_co_u32_e32 v138, vcc, 0xe000, v138
	s_nop 1
	v_addc_co_u32_e32 v139, vcc, 0, v139, vcc
	global_load_dword v154, v[138:139], off nt
	s_branch .LBB0_262

.LBB0_282:
	s_waitcnt lgkmcnt(0)
	s_ashr_i32 s25, s24, 31
	v_add_u32_e32 v158, s5, v145
	s_lshl_b64 s[6:7], s[24:25], 11
	v_ashrrev_i32_e32 v159, 31, v158
	ds_read2_b32 v[136:137], v146 offset1:65
	v_lshl_add_u64 v[158:159], s[6:7], 0, v[158:159]
	s_waitcnt lgkmcnt(0)
	v_cvt_pk_bf16_f32 v136, v136, v137
	ds_read2_b32 v[138:139], v146 offset0:130 offset1:195
	v_add_u32_e32 v154, 0x400, v146
	v_lshlrev_b64 v[158:159], 7, v[158:159]
	s_waitcnt lgkmcnt(0)
	v_cvt_pk_bf16_f32 v137, v138, v139
	ds_read2_b32 v[138:139], v154 offset0:4 offset1:69
	v_lshl_add_u64 v[158:159], v[134:135], 0, v[158:159]
	s_waitcnt lgkmcnt(0)
	v_cvt_pk_bf16_f32 v138, v138, v139
	ds_read2_b32 v[156:157], v154 offset0:134 offset1:199
	s_waitcnt lgkmcnt(0)
	v_cvt_pk_bf16_f32 v139, v156, v157
	global_store_dwordx4 v[158:159], v[136:139], off
	v_add_u32_e32 v158, s5, v147
	v_ashrrev_i32_e32 v159, 31, v158
	v_lshl_add_u64 v[158:159], s[6:7], 0, v[158:159]
	ds_read2_b32 v[156:157], v146 offset0:8 offset1:73
	s_waitcnt lgkmcnt(0)
	v_cvt_pk_bf16_f32 v136, v156, v157
	ds_read2_b32 v[138:139], v146 offset0:138 offset1:203
	v_lshlrev_b64 v[158:159], 7, v[158:159]
	s_waitcnt lgkmcnt(0)
	v_cvt_pk_bf16_f32 v137, v138, v139
	ds_read2_b32 v[138:139], v154 offset0:12 offset1:77
	v_lshl_add_u64 v[158:159], v[134:135], 0, v[158:159]
	s_waitcnt lgkmcnt(0)
	v_cvt_pk_bf16_f32 v138, v138, v139
	ds_read2_b32 v[156:157], v154 offset0:142 offset1:207
	s_waitcnt lgkmcnt(0)
	v_cvt_pk_bf16_f32 v139, v156, v157
	global_store_dwordx4 v[158:159], v[136:139], off
	v_add_u32_e32 v158, s5, v148
	v_ashrrev_i32_e32 v159, 31, v158
	v_lshl_add_u64 v[158:159], s[6:7], 0, v[158:159]
	ds_read2_b32 v[156:157], v146 offset0:16 offset1:81
	s_waitcnt lgkmcnt(0)
	v_cvt_pk_bf16_f32 v136, v156, v157
	ds_read2_b32 v[138:139], v146 offset0:146 offset1:211
	v_lshlrev_b64 v[158:159], 7, v[158:159]
	s_waitcnt lgkmcnt(0)
	v_cvt_pk_bf16_f32 v137, v138, v139
	ds_read2_b32 v[138:139], v154 offset0:20 offset1:85
	v_lshl_add_u64 v[158:159], v[134:135], 0, v[158:159]
	s_waitcnt lgkmcnt(0)
	v_cvt_pk_bf16_f32 v138, v138, v139
	ds_read2_b32 v[156:157], v154 offset0:150 offset1:215
	s_waitcnt lgkmcnt(0)
	v_cvt_pk_bf16_f32 v139, v156, v157
	global_store_dwordx4 v[158:159], v[136:139], off
	v_add_u32_e32 v158, s5, v149
	v_ashrrev_i32_e32 v159, 31, v158
	v_lshl_add_u64 v[158:159], s[6:7], 0, v[158:159]
	ds_read2_b32 v[156:157], v146 offset0:24 offset1:89
	s_waitcnt lgkmcnt(0)
	v_cvt_pk_bf16_f32 v136, v156, v157
	ds_read2_b32 v[138:139], v146 offset0:154 offset1:219
	v_lshlrev_b64 v[158:159], 7, v[158:159]
	s_waitcnt lgkmcnt(0)
	v_cvt_pk_bf16_f32 v137, v138, v139
	ds_read2_b32 v[138:139], v154 offset0:28 offset1:93
	v_lshl_add_u64 v[158:159], v[134:135], 0, v[158:159]
	s_waitcnt lgkmcnt(0)
	v_cvt_pk_bf16_f32 v138, v138, v139
	ds_read2_b32 v[156:157], v154 offset0:158 offset1:223
	s_waitcnt lgkmcnt(0)
	v_cvt_pk_bf16_f32 v139, v156, v157
	global_store_dwordx4 v[158:159], v[136:139], off
	v_add_u32_e32 v158, s5, v150
	v_ashrrev_i32_e32 v159, 31, v158
	v_lshl_add_u64 v[158:159], s[6:7], 0, v[158:159]
	ds_read2_b32 v[156:157], v146 offset0:32 offset1:97
	s_waitcnt lgkmcnt(0)
	v_cvt_pk_bf16_f32 v136, v156, v157
	ds_read2_b32 v[138:139], v146 offset0:162 offset1:227
	v_lshlrev_b64 v[158:159], 7, v[158:159]
	s_waitcnt lgkmcnt(0)
	v_cvt_pk_bf16_f32 v137, v138, v139
	ds_read2_b32 v[138:139], v154 offset0:36 offset1:101
	v_lshl_add_u64 v[158:159], v[134:135], 0, v[158:159]
	s_waitcnt lgkmcnt(0)
	v_cvt_pk_bf16_f32 v138, v138, v139
	ds_read2_b32 v[156:157], v154 offset0:166 offset1:231
	s_waitcnt lgkmcnt(0)
	v_cvt_pk_bf16_f32 v139, v156, v157
	global_store_dwordx4 v[158:159], v[136:139], off
	v_add_u32_e32 v158, s5, v151
	v_ashrrev_i32_e32 v159, 31, v158
	v_lshl_add_u64 v[158:159], s[6:7], 0, v[158:159]
	ds_read2_b32 v[156:157], v146 offset0:40 offset1:105
	s_waitcnt lgkmcnt(0)
	v_cvt_pk_bf16_f32 v136, v156, v157
	ds_read2_b32 v[138:139], v146 offset0:170 offset1:235
	v_lshlrev_b64 v[158:159], 7, v[158:159]
	s_waitcnt lgkmcnt(0)
	v_cvt_pk_bf16_f32 v137, v138, v139
	ds_read2_b32 v[138:139], v154 offset0:44 offset1:109
	v_lshl_add_u64 v[158:159], v[134:135], 0, v[158:159]
	s_waitcnt lgkmcnt(0)
	v_cvt_pk_bf16_f32 v138, v138, v139
	ds_read2_b32 v[156:157], v154 offset0:174 offset1:239
	s_waitcnt lgkmcnt(0)
	v_cvt_pk_bf16_f32 v139, v156, v157
	global_store_dwordx4 v[158:159], v[136:139], off
	v_add_u32_e32 v158, s5, v152
	ds_read2_b32 v[156:157], v146 offset0:48 offset1:113
	s_waitcnt lgkmcnt(0)
	v_cvt_pk_bf16_f32 v136, v156, v157
	ds_read2_b32 v[138:139], v146 offset0:178 offset1:243
	v_ashrrev_i32_e32 v159, 31, v158
	s_waitcnt lgkmcnt(0)
	v_cvt_pk_bf16_f32 v137, v138, v139
	ds_read2_b32 v[138:139], v154 offset0:52 offset1:117
	v_lshl_add_u64 v[158:159], s[6:7], 0, v[158:159]
	s_waitcnt lgkmcnt(0)
	v_cvt_pk_bf16_f32 v138, v138, v139
	ds_read2_b32 v[156:157], v154 offset0:182 offset1:247
	v_lshlrev_b64 v[158:159], 7, v[158:159]
	s_waitcnt lgkmcnt(0)
	v_cvt_pk_bf16_f32 v139, v156, v157
	ds_read2_b32 v[156:157], v146 offset0:56 offset1:121
	v_lshl_add_u64 v[158:159], v[134:135], 0, v[158:159]
	global_store_dwordx4 v[158:159], v[136:139], off
	s_andn2_b64 vcc, exec, s[22:23]
	s_mov_b64 s[22:23], -1
	s_waitcnt lgkmcnt(0)
	v_cvt_pk_bf16_f32 v136, v156, v157
	v_add_u32_e32 v156, s5, v153
	v_ashrrev_i32_e32 v157, 31, v156
	v_lshl_add_u64 v[156:157], s[6:7], 0, v[156:157]
	ds_read2_b32 v[138:139], v146 offset0:186 offset1:251
	v_lshlrev_b64 v[156:157], 7, v[156:157]
	s_waitcnt lgkmcnt(0)
	v_cvt_pk_bf16_f32 v137, v138, v139
	ds_read2_b32 v[138:139], v154 offset0:60 offset1:125
	v_lshl_add_u64 v[156:157], v[134:135], 0, v[156:157]
	s_waitcnt lgkmcnt(0)
	v_cvt_pk_bf16_f32 v138, v138, v139
	ds_read2_b32 v[158:159], v154 offset0:190 offset1:255
	s_waitcnt lgkmcnt(0)
	v_cvt_pk_bf16_f32 v139, v158, v159
	global_store_dwordx4 v[156:157], v[136:139], off
	s_waitcnt lgkmcnt(0)
	s_cbranch_vccnz .LBB0_256
	s_add_i32 s5, s33, s77
	s_cmpk_gt_i32 s5, 0x3ff
	s_cselect_b64 s[22:23], -1, 0
	s_and_b64 vcc, exec, s[22:23]
	s_cbranch_vccnz .LBB0_286
	s_ashr_i32 s6, s5, 31
	s_lshr_b32 s6, s6, 27
	s_add_i32 s6, s5, s6
	s_and_b32 s7, s6, 0xffffffe0
	s_sub_i32 s7, s5, s7
	s_cmp_lt_i32 s7, 0
	s_cbranch_scc1 .LBB0_286
	s_ashr_i32 s6, s6, 5
	s_waitcnt vmcnt(23)
	v_lshl_add_u32 v2, s6, 6, v141
	v_ashrrev_i32_e32 v3, 31, v2
	v_lshlrev_b64 v[2:3], 13, v[2:3]
	s_lshl_b32 s8, s7, 6
	v_lshl_add_u64 v[2:3], s[20:21], 0, v[2:3]
	v_lshl_add_u64 v[2:3], s[8:9], 2, v[2:3]
	s_waitcnt vmcnt(8)
	v_lshl_add_u64 v[62:63], v[132:133], 2, v[2:3]
	v_add_co_u32_e32 v6, vcc, 0x8000, v62
	s_nop 1
	v_addc_co_u32_e32 v7, vcc, 0, v63, vcc
	v_add_co_u32_e32 v10, vcc, 0x10000, v62
	global_load_dwordx4 v[2:5], v[62:63], off nt
	s_nop 0
	global_load_dwordx4 v[6:9], v[6:7], off nt
	v_addc_co_u32_e32 v11, vcc, 0, v63, vcc
	v_add_co_u32_e32 v14, vcc, 0x18000, v62
	s_nop 1
	v_addc_co_u32_e32 v15, vcc, 0, v63, vcc
	v_add_co_u32_e32 v18, vcc, s45, v62
	global_load_dwordx4 v[10:13], v[10:11], off nt
	s_nop 0
	global_load_dwordx4 v[14:17], v[14:15], off nt
	v_addc_co_u32_e32 v19, vcc, 0, v63, vcc
	v_add_co_u32_e32 v22, vcc, 0x28000, v62
	s_nop 1
	v_addc_co_u32_e32 v23, vcc, 0, v63, vcc
	v_add_co_u32_e32 v26, vcc, 0x30000, v62
	global_load_dwordx4 v[18:21], v[18:19], off nt
	s_nop 0
	global_load_dwordx4 v[22:25], v[22:23], off nt
	v_addc_co_u32_e32 v27, vcc, 0, v63, vcc
	v_add_co_u32_e32 v30, vcc, 0x38000, v62
	s_nop 1
	v_addc_co_u32_e32 v31, vcc, 0, v63, vcc
	v_add_co_u32_e32 v34, vcc, 0x40000, v62
	global_load_dwordx4 v[26:29], v[26:27], off nt
	s_nop 0
	global_load_dwordx4 v[30:33], v[30:31], off nt
	v_addc_co_u32_e32 v35, vcc, 0, v63, vcc
	v_add_co_u32_e32 v38, vcc, 0x48000, v62
	s_nop 1
	v_addc_co_u32_e32 v39, vcc, 0, v63, vcc
	v_add_co_u32_e32 v42, vcc, 0x50000, v62
	global_load_dwordx4 v[34:37], v[34:35], off nt
	s_nop 0
	global_load_dwordx4 v[38:41], v[38:39], off nt
	v_addc_co_u32_e32 v43, vcc, 0, v63, vcc
	v_add_co_u32_e32 v46, vcc, 0x58000, v62
	s_nop 1
	v_addc_co_u32_e32 v47, vcc, 0, v63, vcc
	v_add_co_u32_e32 v50, vcc, 0x60000, v62
	global_load_dwordx4 v[42:45], v[42:43], off nt
	s_nop 0
	global_load_dwordx4 v[46:49], v[46:47], off nt
	v_addc_co_u32_e32 v51, vcc, 0, v63, vcc
	v_add_co_u32_e32 v54, vcc, 0x68000, v62
	s_nop 1
	v_addc_co_u32_e32 v55, vcc, 0, v63, vcc
	v_add_co_u32_e32 v64, vcc, 0x70000, v62
	global_load_dwordx4 v[50:53], v[50:51], off nt
	s_nop 0
	global_load_dwordx4 v[54:57], v[54:55], off nt
	v_addc_co_u32_e32 v65, vcc, 0, v63, vcc
	v_add_co_u32_e32 v70, vcc, 0x78000, v62
	s_nop 1
	v_addc_co_u32_e32 v71, vcc, 0, v63, vcc
	global_load_dwordx4 v[62:65], v[64:65], off nt
	s_nop 0
	global_load_dwordx4 v[70:73], v[70:71], off nt

.LBB0_289:
	v_mov_b32_e32 v155, 0
	v_lshl_add_u64 v[138:139], v[136:137], 0, s[26:27]
	v_mov_b32_e32 v156, 0
	s_and_saveexec_b64 s[28:29], s[6:7]
	s_cbranch_execz .LBB0_291
	global_load_dword v156, v[138:139], off nt
.LBB0_291:
	s_or_b64 exec, exec, s[28:29]
	s_waitcnt vmcnt(0)
	ds_write_b32 v130, v156
	s_and_saveexec_b64 s[28:29], s[6:7]
	s_cbranch_execz .LBB0_293
	v_add_co_u32_e32 v156, vcc, 0x2000, v138
	s_nop 1
	v_addc_co_u32_e32 v157, vcc, 0, v139, vcc
	global_load_dword v155, v[156:157], off nt
.LBB0_293:
	s_or_b64 exec, exec, s[28:29]
	s_waitcnt vmcnt(0)
	ds_write_b32 v130, v155 offset:260
	v_mov_b32_e32 v155, 0
	v_mov_b32_e32 v156, 0
	s_and_saveexec_b64 s[28:29], s[6:7]
	s_cbranch_execz .LBB0_295
	v_add_co_u32_e32 v156, vcc, 0x4000, v138
	s_nop 1
	v_addc_co_u32_e32 v157, vcc, 0, v139, vcc
	global_load_dword v156, v[156:157], off nt
.LBB0_295:
	s_or_b64 exec, exec, s[28:29]
	s_waitcnt vmcnt(0)
	ds_write_b32 v130, v156 offset:520
	s_and_saveexec_b64 s[28:29], s[6:7]
	s_cbranch_execz .LBB0_297
	v_add_co_u32_e32 v156, vcc, 0x6000, v138
	s_nop 1
	v_addc_co_u32_e32 v157, vcc, 0, v139, vcc
	global_load_dword v155, v[156:157], off nt
.LBB0_297:
	s_or_b64 exec, exec, s[28:29]
	s_waitcnt vmcnt(0)
	ds_write_b32 v130, v155 offset:780
	v_mov_b32_e32 v155, 0
	v_mov_b32_e32 v156, 0
	s_and_saveexec_b64 s[28:29], s[6:7]
	s_cbranch_execz .LBB0_299
	v_add_co_u32_e32 v156, vcc, 0x8000, v138
	s_nop 1
	v_addc_co_u32_e32 v157, vcc, 0, v139, vcc
	global_load_dword v156, v[156:157], off nt
.LBB0_299:
	s_or_b64 exec, exec, s[28:29]
	s_waitcnt vmcnt(0)
	ds_write_b32 v130, v156 offset:1040
	s_and_saveexec_b64 s[28:29], s[6:7]
	s_cbranch_execz .LBB0_301
	v_add_co_u32_e32 v156, vcc, 0xa000, v138
	s_nop 1
	v_addc_co_u32_e32 v157, vcc, 0, v139, vcc
	global_load_dword v155, v[156:157], off nt
.LBB0_301:
	s_or_b64 exec, exec, s[28:29]
	s_waitcnt vmcnt(0)
	ds_write_b32 v130, v155 offset:1300
	v_mov_b32_e32 v155, 0
	v_mov_b32_e32 v156, 0
	s_and_saveexec_b64 s[28:29], s[6:7]
	s_cbranch_execz .LBB0_303
	v_add_co_u32_e32 v156, vcc, 0xc000, v138
	s_nop 1
	v_addc_co_u32_e32 v157, vcc, 0, v139, vcc
	global_load_dword v156, v[156:157], off nt
.LBB0_303:
	s_or_b64 exec, exec, s[28:29]
	s_waitcnt vmcnt(0)
	ds_write_b32 v130, v156 offset:1560
	s_and_saveexec_b64 s[28:29], s[6:7]
	s_cbranch_execz .LBB0_288
	v_add_co_u32_e32 v138, vcc, 0xe000, v138
	s_nop 1
	v_addc_co_u32_e32 v139, vcc, 0, v139, vcc
	global_load_dword v155, v[138:139], off nt
	s_branch .LBB0_288

.LBB0_311:
	s_andn2_b64 vcc, exec, s[6:7]
	s_cbranch_vccnz .LBB0_313
	s_ashr_i32 s4, s4, 6
	v_lshl_add_u32 v2, s4, 6, v60
	v_ashrrev_i32_e32 v3, 31, v2
	v_lshlrev_b64 v[2:3], 14, v[2:3]
	s_lshl_b32 s8, s5, 6
	v_lshl_add_u64 v[2:3], s[12:13], 0, v[2:3]
	v_lshl_add_u64 v[2:3], s[8:9], 2, v[2:3]
	v_lshlrev_b32_e32 v130, 2, v58
	s_waitcnt vmcnt(0)
	v_lshl_add_u64 v[62:63], v[2:3], 0, v[130:131]
	v_add_co_u32_e32 v6, vcc, s58, v62
	v_mov_b32_e32 v59, v131
	s_nop 0
	v_addc_co_u32_e32 v7, vcc, 0, v63, vcc
	v_add_co_u32_e32 v10, vcc, s45, v62
	global_load_dwordx4 v[2:5], v[62:63], off nt
	s_nop 0
	global_load_dwordx4 v[6:9], v[6:7], off nt
	v_addc_co_u32_e32 v11, vcc, 0, v63, vcc
	v_add_co_u32_e32 v14, vcc, s61, v62
	v_mov_b64_e32 v[132:133], v[58:59]
	s_nop 0
	v_addc_co_u32_e32 v15, vcc, 0, v63, vcc
	v_add_co_u32_e32 v18, vcc, s63, v62
	global_load_dwordx4 v[10:13], v[10:11], off nt
	s_nop 0
	global_load_dwordx4 v[14:17], v[14:15], off nt
	v_addc_co_u32_e32 v19, vcc, 0, v63, vcc
	v_add_co_u32_e32 v22, vcc, s67, v62
	v_mov_b32_e32 v130, v58
	s_nop 0
	v_addc_co_u32_e32 v23, vcc, 0, v63, vcc
	v_add_co_u32_e32 v26, vcc, s68, v62
	global_load_dwordx4 v[18:21], v[18:19], off nt
	s_nop 0
	global_load_dwordx4 v[22:25], v[22:23], off nt
	v_addc_co_u32_e32 v27, vcc, 0, v63, vcc
	v_add_co_u32_e32 v30, vcc, s69, v62
	v_mov_b32_e32 v140, v60
	s_nop 0
	v_addc_co_u32_e32 v31, vcc, 0, v63, vcc
	v_add_co_u32_e32 v34, vcc, s70, v62
	global_load_dwordx4 v[26:29], v[26:27], off nt
	s_nop 0
	global_load_dwordx4 v[30:33], v[30:31], off nt
	v_addc_co_u32_e32 v35, vcc, 0, v63, vcc
	v_add_co_u32_e32 v38, vcc, s71, v62
	s_nop 1
	v_addc_co_u32_e32 v39, vcc, 0, v63, vcc
	v_add_co_u32_e32 v42, vcc, 0xa0000, v62
	global_load_dwordx4 v[34:37], v[34:35], off nt
	s_nop 0
	global_load_dwordx4 v[38:41], v[38:39], off nt
	v_addc_co_u32_e32 v43, vcc, 0, v63, vcc
	v_add_co_u32_e32 v46, vcc, 0xb0000, v62
	s_nop 1
	v_addc_co_u32_e32 v47, vcc, 0, v63, vcc
	v_add_co_u32_e32 v50, vcc, 0xc0000, v62
	global_load_dwordx4 v[42:45], v[42:43], off nt
	s_nop 0
	global_load_dwordx4 v[46:49], v[46:47], off nt
	v_addc_co_u32_e32 v51, vcc, 0, v63, vcc
	v_add_co_u32_e32 v54, vcc, 0xd0000, v62
	s_nop 1
	v_addc_co_u32_e32 v55, vcc, 0, v63, vcc
	v_add_co_u32_e32 v64, vcc, 0xe0000, v62
	global_load_dwordx4 v[50:53], v[50:51], off nt
	s_nop 0
	global_load_dwordx4 v[54:57], v[54:55], off nt
	v_addc_co_u32_e32 v65, vcc, 0, v63, vcc
	v_add_co_u32_e32 v62, vcc, 0xf0000, v62
	s_nop 1
	v_addc_co_u32_e32 v63, vcc, 0, v63, vcc
	global_load_dwordx4 v[66:69], v[64:65], off nt
	global_load_dwordx4 v[70:73], v[62:63], off nt

.LBB0_316:
	s_add_i32 s4, s2, s77
	s_cmpk_lt_i32 s4, 0x800
	s_cselect_b64 s[22:23], -1, 0
	s_cmpk_gt_i32 s4, 0x7ff
	s_cbranch_scc1 .LBB0_319
	s_ashr_i32 s5, s4, 31
	s_lshr_b32 s5, s5, 26
	s_add_i32 s5, s4, s5
	s_andn2_b32 s5, s5, 63
	s_sub_i32 s6, s4, s5
	s_cmp_lt_i32 s6, 0
	s_cbranch_scc1 .LBB0_319
	s_waitcnt vmcnt(23)
	v_add_u32_e32 v58, s5, v140
	v_ashrrev_i32_e32 v59, 31, v58
	v_lshlrev_b64 v[58:59], 14, v[58:59]
	s_lshl_b32 s8, s6, 6
	v_lshl_add_u64 v[58:59], s[12:13], 0, v[58:59]
	v_lshl_add_u64 v[58:59], s[8:9], 2, v[58:59]
	s_waitcnt vmcnt(9)
	v_lshl_add_u64 v[122:123], v[132:133], 2, v[58:59]
	s_waitcnt vmcnt(0)
	v_add_co_u32_e32 v62, vcc, 0x10000, v122
	s_nop 1
	v_addc_co_u32_e32 v63, vcc, 0, v123, vcc
	v_add_co_u32_e32 v74, vcc, s45, v122
	global_load_dwordx4 v[58:61], v[122:123], off nt
	s_nop 0
	global_load_dwordx4 v[62:65], v[62:63], off nt
	v_addc_co_u32_e32 v75, vcc, 0, v123, vcc
	v_add_co_u32_e32 v78, vcc, 0x30000, v122
	s_nop 1
	v_addc_co_u32_e32 v79, vcc, 0, v123, vcc
	v_add_co_u32_e32 v82, vcc, 0x40000, v122
	global_load_dwordx4 v[74:77], v[74:75], off nt
	s_nop 0
	global_load_dwordx4 v[78:81], v[78:79], off nt
	v_addc_co_u32_e32 v83, vcc, 0, v123, vcc
	v_add_co_u32_e32 v86, vcc, 0x50000, v122
	s_nop 1
	v_addc_co_u32_e32 v87, vcc, 0, v123, vcc
	v_add_co_u32_e32 v90, vcc, 0x60000, v122
	global_load_dwordx4 v[82:85], v[82:83], off nt
	s_nop 0
	global_load_dwordx4 v[86:89], v[86:87], off nt
	v_addc_co_u32_e32 v91, vcc, 0, v123, vcc
	v_add_co_u32_e32 v94, vcc, 0x70000, v122
	s_nop 1
	v_addc_co_u32_e32 v95, vcc, 0, v123, vcc
	v_add_co_u32_e32 v98, vcc, 0x80000, v122
	global_load_dwordx4 v[90:93], v[90:91], off nt
	s_nop 0
	global_load_dwordx4 v[94:97], v[94:95], off nt
	v_addc_co_u32_e32 v99, vcc, 0, v123, vcc
	v_add_co_u32_e32 v102, vcc, 0x90000, v122
	s_nop 1
	v_addc_co_u32_e32 v103, vcc, 0, v123, vcc
	v_add_co_u32_e32 v106, vcc, 0xa0000, v122
	global_load_dwordx4 v[98:101], v[98:99], off nt
	s_nop 0
	global_load_dwordx4 v[102:105], v[102:103], off nt
	v_addc_co_u32_e32 v107, vcc, 0, v123, vcc
	v_add_co_u32_e32 v110, vcc, 0xb0000, v122
	s_nop 1
	v_addc_co_u32_e32 v111, vcc, 0, v123, vcc
	v_add_co_u32_e32 v114, vcc, 0xc0000, v122
	global_load_dwordx4 v[106:109], v[106:107], off nt
	s_nop 0
	global_load_dwordx4 v[110:113], v[110:111], off nt
	v_addc_co_u32_e32 v115, vcc, 0, v123, vcc
	v_add_co_u32_e32 v118, vcc, 0xd0000, v122
	s_nop 1
	v_addc_co_u32_e32 v119, vcc, 0, v123, vcc
	v_add_co_u32_e32 v124, vcc, 0xe0000, v122
	global_load_dwordx4 v[114:117], v[114:115], off nt
	s_nop 0
	global_load_dwordx4 v[118:121], v[118:119], off nt
	v_addc_co_u32_e32 v125, vcc, 0, v123, vcc
	v_add_co_u32_e32 v126, vcc, 0xf0000, v122
	s_nop 1
	v_addc_co_u32_e32 v127, vcc, 0, v123, vcc
	global_load_dwordx4 v[122:125], v[124:125], off nt
	s_nop 0
	global_load_dwordx4 v[126:129], v[126:127], off nt

.LBB0_322:
	v_mov_b32_e32 v153, 0
	v_lshl_add_u64 v[138:139], v[136:137], 0, s[26:27]
	v_mov_b32_e32 v154, 0
	s_and_saveexec_b64 s[28:29], s[6:7]
	s_cbranch_execz .LBB0_324
	global_load_dword v154, v[138:139], off nt
.LBB0_324:
	s_or_b64 exec, exec, s[28:29]
	s_waitcnt vmcnt(0)
	ds_write_b32 v130, v154
	s_and_saveexec_b64 s[28:29], s[6:7]
	s_cbranch_execz .LBB0_326
	v_add_co_u32_e32 v154, vcc, 0x4000, v138
	s_nop 1
	v_addc_co_u32_e32 v155, vcc, 0, v139, vcc
	global_load_dword v153, v[154:155], off nt
.LBB0_326:
	s_or_b64 exec, exec, s[28:29]
	s_waitcnt vmcnt(0)
	ds_write_b32 v130, v153 offset:260
	v_mov_b32_e32 v153, 0
	v_mov_b32_e32 v154, 0
	s_and_saveexec_b64 s[28:29], s[6:7]
	s_cbranch_execz .LBB0_328
	v_add_co_u32_e32 v154, vcc, 0x8000, v138
	s_nop 1
	v_addc_co_u32_e32 v155, vcc, 0, v139, vcc
	global_load_dword v154, v[154:155], off nt
.LBB0_328:
	s_or_b64 exec, exec, s[28:29]
	s_waitcnt vmcnt(0)
	ds_write_b32 v130, v154 offset:520
	s_and_saveexec_b64 s[28:29], s[6:7]
	s_cbranch_execz .LBB0_330
	v_add_co_u32_e32 v154, vcc, 0xc000, v138
	s_nop 1
	v_addc_co_u32_e32 v155, vcc, 0, v139, vcc
	global_load_dword v153, v[154:155], off nt
.LBB0_330:
	s_or_b64 exec, exec, s[28:29]
	s_waitcnt vmcnt(0)
	ds_write_b32 v130, v153 offset:780
	v_mov_b32_e32 v153, 0
	v_mov_b32_e32 v154, 0
	s_and_saveexec_b64 s[28:29], s[6:7]
	s_cbranch_execz .LBB0_332
	v_add_co_u32_e32 v154, vcc, 0x10000, v138
	s_nop 1
	v_addc_co_u32_e32 v155, vcc, 0, v139, vcc
	global_load_dword v154, v[154:155], off nt
.LBB0_332:
	s_or_b64 exec, exec, s[28:29]
	s_waitcnt vmcnt(0)
	ds_write_b32 v130, v154 offset:1040
	s_and_saveexec_b64 s[28:29], s[6:7]
	s_cbranch_execz .LBB0_334
	v_add_co_u32_e32 v154, vcc, 0x14000, v138
	s_nop 1
	v_addc_co_u32_e32 v155, vcc, 0, v139, vcc
	global_load_dword v153, v[154:155], off nt
.LBB0_334:
	s_or_b64 exec, exec, s[28:29]
	s_waitcnt vmcnt(0)
	ds_write_b32 v130, v153 offset:1300
	v_mov_b32_e32 v153, 0
	v_mov_b32_e32 v154, 0
	s_and_saveexec_b64 s[28:29], s[6:7]
	s_cbranch_execz .LBB0_336
	v_add_co_u32_e32 v154, vcc, 0x18000, v138
	s_nop 1
	v_addc_co_u32_e32 v155, vcc, 0, v139, vcc
	global_load_dword v154, v[154:155], off nt
.LBB0_336:
	s_or_b64 exec, exec, s[28:29]
	s_waitcnt vmcnt(0)
	ds_write_b32 v130, v154 offset:1560
	s_and_saveexec_b64 s[28:29], s[6:7]
	s_cbranch_execz .LBB0_321
	v_add_co_u32_e32 v138, vcc, 0x1c000, v138
	s_nop 1
	v_addc_co_u32_e32 v139, vcc, 0, v139, vcc
	global_load_dword v153, v[138:139], off nt
	s_branch .LBB0_321

.LBB0_341:
	s_waitcnt lgkmcnt(0)
	v_add_u32_e32 v158, s2, v144
	v_ashrrev_i32_e32 v159, 31, v158
	ds_read2_b32 v[136:137], v145 offset1:65
	v_mov_b32_e32 v155, s25
	v_or_b32_e32 v154, s24, v134
	v_lshlrev_b64 v[158:159], 12, v[158:159]
	s_waitcnt lgkmcnt(0)
	v_cvt_pk_bf16_f32 v136, v136, v137
	ds_read2_b32 v[138:139], v145 offset0:130 offset1:195
	v_add_u32_e32 v153, 0x400, v145
	v_lshlrev_b64 v[154:155], 1, v[154:155]
	v_lshl_add_u64 v[158:159], s[20:21], 0, v[158:159]
	s_waitcnt lgkmcnt(0)
	v_cvt_pk_bf16_f32 v137, v138, v139
	ds_read2_b32 v[138:139], v153 offset0:4 offset1:69
	v_lshl_add_u64 v[158:159], v[158:159], 0, v[154:155]
	s_waitcnt lgkmcnt(0)
	v_cvt_pk_bf16_f32 v138, v138, v139
	ds_read2_b32 v[156:157], v153 offset0:134 offset1:199
	s_waitcnt lgkmcnt(0)
	v_cvt_pk_bf16_f32 v139, v156, v157
	global_store_dwordx4 v[158:159], v[136:139], off
	v_add_u32_e32 v158, s2, v146
	v_ashrrev_i32_e32 v159, 31, v158
	v_lshlrev_b64 v[158:159], 12, v[158:159]
	ds_read2_b32 v[156:157], v145 offset0:8 offset1:73
	s_waitcnt lgkmcnt(0)
	v_cvt_pk_bf16_f32 v136, v156, v157
	ds_read2_b32 v[138:139], v145 offset0:138 offset1:203
	v_lshl_add_u64 v[158:159], s[20:21], 0, v[158:159]
	s_waitcnt lgkmcnt(0)
	v_cvt_pk_bf16_f32 v137, v138, v139
	ds_read2_b32 v[138:139], v153 offset0:12 offset1:77
	v_lshl_add_u64 v[158:159], v[158:159], 0, v[154:155]
	s_waitcnt lgkmcnt(0)
	v_cvt_pk_bf16_f32 v138, v138, v139
	ds_read2_b32 v[156:157], v153 offset0:142 offset1:207
	s_waitcnt lgkmcnt(0)
	v_cvt_pk_bf16_f32 v139, v156, v157
	global_store_dwordx4 v[158:159], v[136:139], off
	v_add_u32_e32 v158, s2, v147
	v_ashrrev_i32_e32 v159, 31, v158
	v_lshlrev_b64 v[158:159], 12, v[158:159]
	ds_read2_b32 v[156:157], v145 offset0:16 offset1:81
	s_waitcnt lgkmcnt(0)
	v_cvt_pk_bf16_f32 v136, v156, v157
	ds_read2_b32 v[138:139], v145 offset0:146 offset1:211
	v_lshl_add_u64 v[158:159], s[20:21], 0, v[158:159]
	s_waitcnt lgkmcnt(0)
	v_cvt_pk_bf16_f32 v137, v138, v139
	ds_read2_b32 v[138:139], v153 offset0:20 offset1:85
	v_lshl_add_u64 v[158:159], v[158:159], 0, v[154:155]
	s_waitcnt lgkmcnt(0)
	v_cvt_pk_bf16_f32 v138, v138, v139
	ds_read2_b32 v[156:157], v153 offset0:150 offset1:215
	s_waitcnt lgkmcnt(0)
	v_cvt_pk_bf16_f32 v139, v156, v157
	global_store_dwordx4 v[158:159], v[136:139], off
	v_add_u32_e32 v158, s2, v148
	v_ashrrev_i32_e32 v159, 31, v158
	v_lshlrev_b64 v[158:159], 12, v[158:159]
	ds_read2_b32 v[156:157], v145 offset0:24 offset1:89
	s_waitcnt lgkmcnt(0)
	v_cvt_pk_bf16_f32 v136, v156, v157
	ds_read2_b32 v[138:139], v145 offset0:154 offset1:219
	v_lshl_add_u64 v[158:159], s[20:21], 0, v[158:159]
	s_waitcnt lgkmcnt(0)
	v_cvt_pk_bf16_f32 v137, v138, v139
	ds_read2_b32 v[138:139], v153 offset0:28 offset1:93
	v_lshl_add_u64 v[158:159], v[158:159], 0, v[154:155]
	s_waitcnt lgkmcnt(0)
	v_cvt_pk_bf16_f32 v138, v138, v139
	ds_read2_b32 v[156:157], v153 offset0:158 offset1:223
	s_waitcnt lgkmcnt(0)
	v_cvt_pk_bf16_f32 v139, v156, v157
	global_store_dwordx4 v[158:159], v[136:139], off
	v_add_u32_e32 v158, s2, v149
	v_ashrrev_i32_e32 v159, 31, v158
	v_lshlrev_b64 v[158:159], 12, v[158:159]
	ds_read2_b32 v[156:157], v145 offset0:32 offset1:97
	s_waitcnt lgkmcnt(0)
	v_cvt_pk_bf16_f32 v136, v156, v157
	ds_read2_b32 v[138:139], v145 offset0:162 offset1:227
	v_lshl_add_u64 v[158:159], s[20:21], 0, v[158:159]
	s_waitcnt lgkmcnt(0)
	v_cvt_pk_bf16_f32 v137, v138, v139
	ds_read2_b32 v[138:139], v153 offset0:36 offset1:101
	v_lshl_add_u64 v[158:159], v[158:159], 0, v[154:155]
	s_waitcnt lgkmcnt(0)
	v_cvt_pk_bf16_f32 v138, v138, v139
	ds_read2_b32 v[156:157], v153 offset0:166 offset1:231
	s_waitcnt lgkmcnt(0)
	v_cvt_pk_bf16_f32 v139, v156, v157
	global_store_dwordx4 v[158:159], v[136:139], off
	v_add_u32_e32 v158, s2, v150
	v_ashrrev_i32_e32 v159, 31, v158
	v_lshlrev_b64 v[158:159], 12, v[158:159]
	ds_read2_b32 v[156:157], v145 offset0:40 offset1:105
	s_waitcnt lgkmcnt(0)
	v_cvt_pk_bf16_f32 v136, v156, v157
	ds_read2_b32 v[138:139], v145 offset0:170 offset1:235
	v_lshl_add_u64 v[158:159], s[20:21], 0, v[158:159]
	s_waitcnt lgkmcnt(0)
	v_cvt_pk_bf16_f32 v137, v138, v139
	ds_read2_b32 v[138:139], v153 offset0:44 offset1:109
	v_lshl_add_u64 v[158:159], v[158:159], 0, v[154:155]
	s_waitcnt lgkmcnt(0)
	v_cvt_pk_bf16_f32 v138, v138, v139
	ds_read2_b32 v[156:157], v153 offset0:174 offset1:239
	s_waitcnt lgkmcnt(0)
	v_cvt_pk_bf16_f32 v139, v156, v157
	global_store_dwordx4 v[158:159], v[136:139], off
	v_add_u32_e32 v158, s2, v151
	ds_read2_b32 v[156:157], v145 offset0:48 offset1:113
	s_waitcnt lgkmcnt(0)
	v_cvt_pk_bf16_f32 v136, v156, v157
	ds_read2_b32 v[138:139], v145 offset0:178 offset1:243
	v_ashrrev_i32_e32 v159, 31, v158
	s_waitcnt lgkmcnt(0)
	v_cvt_pk_bf16_f32 v137, v138, v139
	ds_read2_b32 v[138:139], v153 offset0:52 offset1:117
	v_lshlrev_b64 v[158:159], 12, v[158:159]
	s_waitcnt lgkmcnt(0)
	v_cvt_pk_bf16_f32 v138, v138, v139
	ds_read2_b32 v[156:157], v153 offset0:182 offset1:247
	v_lshl_add_u64 v[158:159], s[20:21], 0, v[158:159]
	s_waitcnt lgkmcnt(0)
	v_cvt_pk_bf16_f32 v139, v156, v157
	ds_read2_b32 v[156:157], v145 offset0:56 offset1:121
	v_lshl_add_u64 v[158:159], v[158:159], 0, v[154:155]
	global_store_dwordx4 v[158:159], v[136:139], off
	s_andn2_b64 vcc, exec, s[22:23]
	s_mov_b64 s[22:23], -1
	s_waitcnt lgkmcnt(0)
	v_cvt_pk_bf16_f32 v136, v156, v157
	v_add_u32_e32 v156, s2, v152
	v_ashrrev_i32_e32 v157, 31, v156
	v_lshlrev_b64 v[156:157], 12, v[156:157]
	ds_read2_b32 v[138:139], v145 offset0:186 offset1:251
	v_lshl_add_u64 v[156:157], s[20:21], 0, v[156:157]
	s_waitcnt lgkmcnt(0)
	v_cvt_pk_bf16_f32 v137, v138, v139
	ds_read2_b32 v[138:139], v153 offset0:60 offset1:125
	v_lshl_add_u64 v[154:155], v[156:157], 0, v[154:155]
	s_waitcnt lgkmcnt(0)
	v_cvt_pk_bf16_f32 v138, v138, v139
	ds_read2_b32 v[158:159], v153 offset0:190 offset1:255
	s_waitcnt lgkmcnt(0)
	v_cvt_pk_bf16_f32 v139, v158, v159
	global_store_dwordx4 v[154:155], v[136:139], off
	s_waitcnt lgkmcnt(0)
	s_cbranch_vccnz .LBB0_315
	s_add_i32 s2, s4, s77
	s_cmpk_gt_i32 s2, 0x7ff
	s_cselect_b64 s[22:23], -1, 0
	s_and_b64 vcc, exec, s[22:23]
	s_cbranch_vccnz .LBB0_345
	s_ashr_i32 s5, s2, 31
	s_lshr_b32 s5, s5, 26
	s_add_i32 s5, s2, s5
	s_and_b32 s6, s5, 0xffffffc0
	s_sub_i32 s6, s2, s6
	s_cmp_lt_i32 s6, 0
	s_cbranch_scc1 .LBB0_345
	s_ashr_i32 s5, s5, 6
	s_waitcnt vmcnt(23)
	v_lshl_add_u32 v2, s5, 6, v140
	v_ashrrev_i32_e32 v3, 31, v2
	v_lshlrev_b64 v[2:3], 14, v[2:3]
	s_lshl_b32 s8, s6, 6
	v_lshl_add_u64 v[2:3], s[12:13], 0, v[2:3]
	v_lshl_add_u64 v[2:3], s[8:9], 2, v[2:3]
	s_waitcnt vmcnt(9)
	v_lshl_add_u64 v[66:67], v[132:133], 2, v[2:3]
	v_add_co_u32_e32 v6, vcc, 0x10000, v66
	s_nop 1
	v_addc_co_u32_e32 v7, vcc, 0, v67, vcc
	v_add_co_u32_e32 v10, vcc, s45, v66
	global_load_dwordx4 v[2:5], v[66:67], off nt
	s_nop 0
	global_load_dwordx4 v[6:9], v[6:7], off nt
	v_addc_co_u32_e32 v11, vcc, 0, v67, vcc
	v_add_co_u32_e32 v14, vcc, 0x30000, v66
	s_nop 1
	v_addc_co_u32_e32 v15, vcc, 0, v67, vcc
	v_add_co_u32_e32 v18, vcc, 0x40000, v66
	global_load_dwordx4 v[10:13], v[10:11], off nt
	s_nop 0
	global_load_dwordx4 v[14:17], v[14:15], off nt
	v_addc_co_u32_e32 v19, vcc, 0, v67, vcc
	v_add_co_u32_e32 v22, vcc, 0x50000, v66
	s_nop 1
	v_addc_co_u32_e32 v23, vcc, 0, v67, vcc
	v_add_co_u32_e32 v26, vcc, 0x60000, v66
	global_load_dwordx4 v[18:21], v[18:19], off nt
	s_nop 0
	global_load_dwordx4 v[22:25], v[22:23], off nt
	v_addc_co_u32_e32 v27, vcc, 0, v67, vcc
	v_add_co_u32_e32 v30, vcc, 0x70000, v66
	s_nop 1
	v_addc_co_u32_e32 v31, vcc, 0, v67, vcc
	v_add_co_u32_e32 v34, vcc, 0x80000, v66
	global_load_dwordx4 v[26:29], v[26:27], off nt
	s_nop 0
	global_load_dwordx4 v[30:33], v[30:31], off nt
	v_addc_co_u32_e32 v35, vcc, 0, v67, vcc
	v_add_co_u32_e32 v38, vcc, 0x90000, v66
	s_nop 1
	v_addc_co_u32_e32 v39, vcc, 0, v67, vcc
	v_add_co_u32_e32 v42, vcc, 0xa0000, v66
	global_load_dwordx4 v[34:37], v[34:35], off nt
	s_nop 0
	global_load_dwordx4 v[38:41], v[38:39], off nt
	v_addc_co_u32_e32 v43, vcc, 0, v67, vcc
	v_add_co_u32_e32 v46, vcc, 0xb0000, v66
	s_nop 1
	v_addc_co_u32_e32 v47, vcc, 0, v67, vcc
	v_add_co_u32_e32 v50, vcc, 0xc0000, v66
	global_load_dwordx4 v[42:45], v[42:43], off nt
	s_nop 0
	global_load_dwordx4 v[46:49], v[46:47], off nt
	v_addc_co_u32_e32 v51, vcc, 0, v67, vcc
	v_add_co_u32_e32 v54, vcc, 0xd0000, v66
	s_nop 1
	v_addc_co_u32_e32 v55, vcc, 0, v67, vcc
	v_add_co_u32_e32 v68, vcc, 0xe0000, v66
	global_load_dwordx4 v[50:53], v[50:51], off nt
	s_nop 0
	global_load_dwordx4 v[54:57], v[54:55], off nt
	v_addc_co_u32_e32 v69, vcc, 0, v67, vcc
	s_waitcnt vmcnt(22)
	v_add_co_u32_e32 v70, vcc, 0xf0000, v66
	s_nop 1
	v_addc_co_u32_e32 v71, vcc, 0, v67, vcc
	global_load_dwordx4 v[66:69], v[68:69], off nt
	s_nop 0
	global_load_dwordx4 v[70:73], v[70:71], off nt

.LBB0_350:
	s_or_b64 exec, exec, s[28:29]
	s_waitcnt vmcnt(0)
	ds_write_b32 v130, v155
	s_and_saveexec_b64 s[28:29], s[6:7]
	s_cbranch_execz .LBB0_352
	v_add_co_u32_e32 v154, vcc, 0x4000, v138
	s_nop 1
	v_addc_co_u32_e32 v155, vcc, 0, v139, vcc
	global_load_dword v154, v[154:155], off nt
.LBB0_352:
	s_or_b64 exec, exec, s[28:29]
	s_waitcnt vmcnt(0)
	ds_write_b32 v130, v154 offset:260
	v_mov_b32_e32 v154, 0
	v_mov_b32_e32 v155, 0
	s_and_saveexec_b64 s[28:29], s[6:7]
	s_cbranch_execz .LBB0_354
	v_add_co_u32_e32 v156, vcc, 0x8000, v138
	s_nop 1
	v_addc_co_u32_e32 v157, vcc, 0, v139, vcc
	global_load_dword v155, v[156:157], off nt
.LBB0_354:
	s_or_b64 exec, exec, s[28:29]
	s_waitcnt vmcnt(0)
	ds_write_b32 v130, v155 offset:520
	s_and_saveexec_b64 s[28:29], s[6:7]
	s_cbranch_execz .LBB0_356
	v_add_co_u32_e32 v154, vcc, 0xc000, v138
	s_nop 1
	v_addc_co_u32_e32 v155, vcc, 0, v139, vcc
	global_load_dword v154, v[154:155], off nt
.LBB0_356:
	s_or_b64 exec, exec, s[28:29]
	s_waitcnt vmcnt(0)
	ds_write_b32 v130, v154 offset:780
	v_mov_b32_e32 v154, 0
	v_mov_b32_e32 v155, 0
	s_and_saveexec_b64 s[28:29], s[6:7]
	s_cbranch_execz .LBB0_358
	v_add_co_u32_e32 v156, vcc, 0x10000, v138
	s_nop 1
	v_addc_co_u32_e32 v157, vcc, 0, v139, vcc
	global_load_dword v155, v[156:157], off nt
.LBB0_358:
	s_or_b64 exec, exec, s[28:29]
	s_waitcnt vmcnt(0)
	ds_write_b32 v130, v155 offset:1040
	s_and_saveexec_b64 s[28:29], s[6:7]
	s_cbranch_execz .LBB0_360
	v_add_co_u32_e32 v154, vcc, 0x14000, v138
	s_nop 1
	v_addc_co_u32_e32 v155, vcc, 0, v139, vcc
	global_load_dword v154, v[154:155], off nt
.LBB0_360:
	s_or_b64 exec, exec, s[28:29]
	s_waitcnt vmcnt(0)
	ds_write_b32 v130, v154 offset:1300
	v_mov_b32_e32 v154, 0
	v_mov_b32_e32 v155, 0
	s_and_saveexec_b64 s[28:29], s[6:7]
	s_cbranch_execz .LBB0_362
	v_add_co_u32_e32 v156, vcc, 0x18000, v138
	s_nop 1
	v_addc_co_u32_e32 v157, vcc, 0, v139, vcc
	global_load_dword v155, v[156:157], off nt
.LBB0_362:
	s_or_b64 exec, exec, s[28:29]
	s_waitcnt vmcnt(0)
	ds_write_b32 v130, v155 offset:1560
	s_and_saveexec_b64 s[28:29], s[6:7]
	s_cbranch_execz .LBB0_347
	v_add_co_u32_e32 v138, vcc, 0x1c000, v138
	s_nop 1
	v_addc_co_u32_e32 v139, vcc, 0, v139, vcc
	global_load_dword v154, v[138:139], off nt
	s_branch .LBB0_347

.LBB0_370:
	s_andn2_b64 vcc, exec, s[18:19]
	s_cbranch_vccnz .LBB0_372
	s_ashr_i32 s2, s2, 5
	v_lshl_add_u32 v2, s2, 6, v60
	v_ashrrev_i32_e32 v3, 31, v2
	v_lshlrev_b64 v[2:3], 13, v[2:3]
	s_lshl_b32 s8, s4, 6
	v_lshl_add_u64 v[2:3], s[12:13], 0, v[2:3]
	v_lshl_add_u64 v[2:3], s[8:9], 2, v[2:3]
	v_lshlrev_b32_e32 v130, 2, v58
	s_waitcnt vmcnt(0)
	v_lshl_add_u64 v[62:63], v[2:3], 0, v[130:131]
	v_add_co_u32_e32 v6, vcc, s57, v62
	v_mov_b32_e32 v59, v131
	s_nop 0
	v_addc_co_u32_e32 v7, vcc, 0, v63, vcc
	v_add_co_u32_e32 v10, vcc, s58, v62
	global_load_dwordx4 v[2:5], v[62:63], off nt
	s_nop 0
	global_load_dwordx4 v[6:9], v[6:7], off nt
	v_addc_co_u32_e32 v11, vcc, 0, v63, vcc
	v_add_co_u32_e32 v14, vcc, s59, v62
	v_mov_b64_e32 v[132:133], v[58:59]
	s_nop 0
	v_addc_co_u32_e32 v15, vcc, 0, v63, vcc
	v_add_co_u32_e32 v18, vcc, s45, v62
	global_load_dwordx4 v[10:13], v[10:11], off nt
	s_nop 0
	global_load_dwordx4 v[14:17], v[14:15], off nt
	v_addc_co_u32_e32 v19, vcc, 0, v63, vcc
	v_add_co_u32_e32 v22, vcc, s60, v62
	v_mov_b32_e32 v130, v58
	s_nop 0
	v_addc_co_u32_e32 v23, vcc, 0, v63, vcc
	v_add_co_u32_e32 v26, vcc, s61, v62
	global_load_dwordx4 v[18:21], v[18:19], off nt
	s_nop 0
	global_load_dwordx4 v[22:25], v[22:23], off nt
	v_addc_co_u32_e32 v27, vcc, 0, v63, vcc
	v_add_co_u32_e32 v30, vcc, s62, v62
	v_mov_b32_e32 v140, v60
	s_nop 0
	v_addc_co_u32_e32 v31, vcc, 0, v63, vcc
	v_add_co_u32_e32 v34, vcc, s63, v62
	global_load_dwordx4 v[26:29], v[26:27], off nt
	s_nop 0
	global_load_dwordx4 v[30:33], v[30:31], off nt
	v_addc_co_u32_e32 v35, vcc, 0, v63, vcc
	v_add_co_u32_e32 v38, vcc, s66, v62
	s_nop 1
	v_addc_co_u32_e32 v39, vcc, 0, v63, vcc
	v_add_co_u32_e32 v42, vcc, 0x50000, v62
	global_load_dwordx4 v[34:37], v[34:35], off nt
	s_nop 0
	global_load_dwordx4 v[38:41], v[38:39], off nt
	v_addc_co_u32_e32 v43, vcc, 0, v63, vcc
	v_add_co_u32_e32 v46, vcc, 0x58000, v62
	s_nop 1
	v_addc_co_u32_e32 v47, vcc, 0, v63, vcc
	v_add_co_u32_e32 v50, vcc, 0x60000, v62
	global_load_dwordx4 v[42:45], v[42:43], off nt
	s_nop 0
	global_load_dwordx4 v[46:49], v[46:47], off nt
	v_addc_co_u32_e32 v51, vcc, 0, v63, vcc
	v_add_co_u32_e32 v54, vcc, 0x68000, v62
	s_nop 1
	v_addc_co_u32_e32 v55, vcc, 0, v63, vcc
	v_add_co_u32_e32 v64, vcc, 0x70000, v62
	global_load_dwordx4 v[50:53], v[50:51], off nt
	s_nop 0
	global_load_dwordx4 v[54:57], v[54:55], off nt
	v_addc_co_u32_e32 v65, vcc, 0, v63, vcc
	v_add_co_u32_e32 v62, vcc, 0x78000, v62
	s_nop 1
	v_addc_co_u32_e32 v63, vcc, 0, v63, vcc
	global_load_dwordx4 v[66:69], v[64:65], off nt
	global_load_dwordx4 v[70:73], v[62:63], off nt

.LBB0_375:
	s_add_i32 s24, s5, s77
	s_cmpk_lt_i32 s24, 0x400
	s_cselect_b64 s[16:17], -1, 0
	s_cmpk_gt_i32 s24, 0x3ff
	s_cbranch_scc1 .LBB0_378
	s_ashr_i32 s6, s24, 31
	s_lshr_b32 s6, s6, 27
	s_add_i32 s6, s24, s6
	s_and_b32 s7, s6, 0xffffffe0
	s_sub_i32 s7, s24, s7
	s_cmp_lt_i32 s7, 0
	s_cbranch_scc1 .LBB0_378
	s_lshl_b32 s6, s6, 1
	s_andn2_b32 s6, s6, 63
	s_waitcnt vmcnt(23)
	v_add_u32_e32 v58, s6, v140
	v_ashrrev_i32_e32 v59, 31, v58
	v_lshlrev_b64 v[58:59], 13, v[58:59]
	s_lshl_b32 s8, s7, 6
	v_lshl_add_u64 v[58:59], s[12:13], 0, v[58:59]
	v_lshl_add_u64 v[58:59], s[8:9], 2, v[58:59]
	s_waitcnt vmcnt(9)
	v_lshl_add_u64 v[122:123], v[132:133], 2, v[58:59]
	s_waitcnt vmcnt(0)
	v_add_co_u32_e32 v62, vcc, 0x8000, v122
	s_nop 1
	v_addc_co_u32_e32 v63, vcc, 0, v123, vcc
	v_add_co_u32_e32 v74, vcc, 0x10000, v122
	global_load_dwordx4 v[58:61], v[122:123], off nt
	s_nop 0
	global_load_dwordx4 v[62:65], v[62:63], off nt
	v_addc_co_u32_e32 v75, vcc, 0, v123, vcc
	v_add_co_u32_e32 v78, vcc, 0x18000, v122
	s_nop 1
	v_addc_co_u32_e32 v79, vcc, 0, v123, vcc
	v_add_co_u32_e32 v82, vcc, s45, v122
	global_load_dwordx4 v[74:77], v[74:75], off nt
	s_nop 0
	global_load_dwordx4 v[78:81], v[78:79], off nt
	v_addc_co_u32_e32 v83, vcc, 0, v123, vcc
	v_add_co_u32_e32 v86, vcc, 0x28000, v122
	s_nop 1
	v_addc_co_u32_e32 v87, vcc, 0, v123, vcc
	v_add_co_u32_e32 v90, vcc, 0x30000, v122
	global_load_dwordx4 v[82:85], v[82:83], off nt
	s_nop 0
	global_load_dwordx4 v[86:89], v[86:87], off nt
	v_addc_co_u32_e32 v91, vcc, 0, v123, vcc
	v_add_co_u32_e32 v94, vcc, 0x38000, v122
	s_nop 1
	v_addc_co_u32_e32 v95, vcc, 0, v123, vcc
	v_add_co_u32_e32 v98, vcc, 0x40000, v122
	global_load_dwordx4 v[90:93], v[90:91], off nt
	s_nop 0
	global_load_dwordx4 v[94:97], v[94:95], off nt
	v_addc_co_u32_e32 v99, vcc, 0, v123, vcc
	v_add_co_u32_e32 v102, vcc, 0x48000, v122
	s_nop 1
	v_addc_co_u32_e32 v103, vcc, 0, v123, vcc
	v_add_co_u32_e32 v106, vcc, 0x50000, v122
	global_load_dwordx4 v[98:101], v[98:99], off nt
	s_nop 0
	global_load_dwordx4 v[102:105], v[102:103], off nt
	v_addc_co_u32_e32 v107, vcc, 0, v123, vcc
	v_add_co_u32_e32 v110, vcc, 0x58000, v122
	s_nop 1
	v_addc_co_u32_e32 v111, vcc, 0, v123, vcc
	v_add_co_u32_e32 v114, vcc, 0x60000, v122
	global_load_dwordx4 v[106:109], v[106:107], off nt
	s_nop 0
	global_load_dwordx4 v[110:113], v[110:111], off nt
	v_addc_co_u32_e32 v115, vcc, 0, v123, vcc
	v_add_co_u32_e32 v118, vcc, 0x68000, v122
	s_nop 1
	v_addc_co_u32_e32 v119, vcc, 0, v123, vcc
	v_add_co_u32_e32 v124, vcc, 0x70000, v122
	global_load_dwordx4 v[114:117], v[114:115], off nt
	s_nop 0
	global_load_dwordx4 v[118:121], v[118:119], off nt
	v_addc_co_u32_e32 v125, vcc, 0, v123, vcc
	v_add_co_u32_e32 v126, vcc, 0x78000, v122
	s_nop 1
	v_addc_co_u32_e32 v127, vcc, 0, v123, vcc
	global_load_dwordx4 v[122:125], v[124:125], off nt
	s_nop 0
	global_load_dwordx4 v[126:129], v[126:127], off nt

.LBB0_381:
	v_mov_b32_e32 v153, 0
	v_lshl_add_u64 v[138:139], v[136:137], 0, s[20:21]
	v_mov_b32_e32 v154, 0
	s_and_saveexec_b64 s[22:23], s[6:7]
	s_cbranch_execz .LBB0_383
	global_load_dword v154, v[138:139], off nt
.LBB0_383:
	s_or_b64 exec, exec, s[22:23]
	s_waitcnt vmcnt(0)
	ds_write_b32 v130, v154
	s_and_saveexec_b64 s[22:23], s[6:7]
	s_cbranch_execz .LBB0_385
	v_add_co_u32_e32 v154, vcc, 0x2000, v138
	s_nop 1
	v_addc_co_u32_e32 v155, vcc, 0, v139, vcc
	global_load_dword v153, v[154:155], off nt
.LBB0_385:
	s_or_b64 exec, exec, s[22:23]
	s_waitcnt vmcnt(0)
	ds_write_b32 v130, v153 offset:260
	v_mov_b32_e32 v153, 0
	v_mov_b32_e32 v154, 0
	s_and_saveexec_b64 s[22:23], s[6:7]
	s_cbranch_execz .LBB0_387
	v_add_co_u32_e32 v154, vcc, 0x4000, v138
	s_nop 1
	v_addc_co_u32_e32 v155, vcc, 0, v139, vcc
	global_load_dword v154, v[154:155], off nt
.LBB0_387:
	s_or_b64 exec, exec, s[22:23]
	s_waitcnt vmcnt(0)
	ds_write_b32 v130, v154 offset:520
	s_and_saveexec_b64 s[22:23], s[6:7]
	s_cbranch_execz .LBB0_389
	v_add_co_u32_e32 v154, vcc, 0x6000, v138
	s_nop 1
	v_addc_co_u32_e32 v155, vcc, 0, v139, vcc
	global_load_dword v153, v[154:155], off nt
.LBB0_389:
	s_or_b64 exec, exec, s[22:23]
	s_waitcnt vmcnt(0)
	ds_write_b32 v130, v153 offset:780
	v_mov_b32_e32 v153, 0
	v_mov_b32_e32 v154, 0
	s_and_saveexec_b64 s[22:23], s[6:7]
	s_cbranch_execz .LBB0_391
	v_add_co_u32_e32 v154, vcc, 0x8000, v138
	s_nop 1
	v_addc_co_u32_e32 v155, vcc, 0, v139, vcc
	global_load_dword v154, v[154:155], off nt
.LBB0_391:
	s_or_b64 exec, exec, s[22:23]
	s_waitcnt vmcnt(0)
	ds_write_b32 v130, v154 offset:1040
	s_and_saveexec_b64 s[22:23], s[6:7]
	s_cbranch_execz .LBB0_393
	v_add_co_u32_e32 v154, vcc, 0xa000, v138
	s_nop 1
	v_addc_co_u32_e32 v155, vcc, 0, v139, vcc
	global_load_dword v153, v[154:155], off nt
.LBB0_393:
	s_or_b64 exec, exec, s[22:23]
	s_waitcnt vmcnt(0)
	ds_write_b32 v130, v153 offset:1300
	v_mov_b32_e32 v153, 0
	v_mov_b32_e32 v154, 0
	s_and_saveexec_b64 s[22:23], s[6:7]
	s_cbranch_execz .LBB0_395
	v_add_co_u32_e32 v154, vcc, 0xc000, v138
	s_nop 1
	v_addc_co_u32_e32 v155, vcc, 0, v139, vcc
	global_load_dword v154, v[154:155], off nt
.LBB0_395:
	s_or_b64 exec, exec, s[22:23]
	s_waitcnt vmcnt(0)
	ds_write_b32 v130, v154 offset:1560
	s_and_saveexec_b64 s[22:23], s[6:7]
	s_cbranch_execz .LBB0_380
	v_add_co_u32_e32 v138, vcc, 0xe000, v138
	s_nop 1
	v_addc_co_u32_e32 v139, vcc, 0, v139, vcc
	global_load_dword v153, v[138:139], off nt
	s_branch .LBB0_380

.LBB0_400:
	s_waitcnt lgkmcnt(0)
	v_add_u32_e32 v158, s5, v144
	v_ashrrev_i32_e32 v159, 31, v158
	ds_read2_b32 v[136:137], v145 offset1:65
	v_mov_b32_e32 v155, s19
	v_or_b32_e32 v154, s18, v134
	v_lshlrev_b64 v[158:159], 12, v[158:159]
	s_waitcnt lgkmcnt(0)
	v_cvt_pk_bf16_f32 v136, v136, v137
	ds_read2_b32 v[138:139], v145 offset0:130 offset1:195
	v_add_u32_e32 v153, 0x400, v145
	v_lshlrev_b64 v[154:155], 1, v[154:155]
	v_lshl_add_u64 v[158:159], s[14:15], 0, v[158:159]
	s_waitcnt lgkmcnt(0)
	v_cvt_pk_bf16_f32 v137, v138, v139
	ds_read2_b32 v[138:139], v153 offset0:4 offset1:69
	v_lshl_add_u64 v[158:159], v[158:159], 0, v[154:155]
	s_waitcnt lgkmcnt(0)
	v_cvt_pk_bf16_f32 v138, v138, v139
	ds_read2_b32 v[156:157], v153 offset0:134 offset1:199
	s_waitcnt lgkmcnt(0)
	v_cvt_pk_bf16_f32 v139, v156, v157
	global_store_dwordx4 v[158:159], v[136:139], off
	v_add_u32_e32 v158, s5, v146
	v_ashrrev_i32_e32 v159, 31, v158
	v_lshlrev_b64 v[158:159], 12, v[158:159]
	ds_read2_b32 v[156:157], v145 offset0:8 offset1:73
	s_waitcnt lgkmcnt(0)
	v_cvt_pk_bf16_f32 v136, v156, v157
	ds_read2_b32 v[138:139], v145 offset0:138 offset1:203
	v_lshl_add_u64 v[158:159], s[14:15], 0, v[158:159]
	s_waitcnt lgkmcnt(0)
	v_cvt_pk_bf16_f32 v137, v138, v139
	ds_read2_b32 v[138:139], v153 offset0:12 offset1:77
	v_lshl_add_u64 v[158:159], v[158:159], 0, v[154:155]
	s_waitcnt lgkmcnt(0)
	v_cvt_pk_bf16_f32 v138, v138, v139
	ds_read2_b32 v[156:157], v153 offset0:142 offset1:207
	s_waitcnt lgkmcnt(0)
	v_cvt_pk_bf16_f32 v139, v156, v157
	global_store_dwordx4 v[158:159], v[136:139], off
	v_add_u32_e32 v158, s5, v147
	v_ashrrev_i32_e32 v159, 31, v158
	v_lshlrev_b64 v[158:159], 12, v[158:159]
	ds_read2_b32 v[156:157], v145 offset0:16 offset1:81
	s_waitcnt lgkmcnt(0)
	v_cvt_pk_bf16_f32 v136, v156, v157
	ds_read2_b32 v[138:139], v145 offset0:146 offset1:211
	v_lshl_add_u64 v[158:159], s[14:15], 0, v[158:159]
	s_waitcnt lgkmcnt(0)
	v_cvt_pk_bf16_f32 v137, v138, v139
	ds_read2_b32 v[138:139], v153 offset0:20 offset1:85
	v_lshl_add_u64 v[158:159], v[158:159], 0, v[154:155]
	s_waitcnt lgkmcnt(0)
	v_cvt_pk_bf16_f32 v138, v138, v139
	ds_read2_b32 v[156:157], v153 offset0:150 offset1:215
	s_waitcnt lgkmcnt(0)
	v_cvt_pk_bf16_f32 v139, v156, v157
	global_store_dwordx4 v[158:159], v[136:139], off
	v_add_u32_e32 v158, s5, v148
	v_ashrrev_i32_e32 v159, 31, v158
	v_lshlrev_b64 v[158:159], 12, v[158:159]
	ds_read2_b32 v[156:157], v145 offset0:24 offset1:89
	s_waitcnt lgkmcnt(0)
	v_cvt_pk_bf16_f32 v136, v156, v157
	ds_read2_b32 v[138:139], v145 offset0:154 offset1:219
	v_lshl_add_u64 v[158:159], s[14:15], 0, v[158:159]
	s_waitcnt lgkmcnt(0)
	v_cvt_pk_bf16_f32 v137, v138, v139
	ds_read2_b32 v[138:139], v153 offset0:28 offset1:93
	v_lshl_add_u64 v[158:159], v[158:159], 0, v[154:155]
	s_waitcnt lgkmcnt(0)
	v_cvt_pk_bf16_f32 v138, v138, v139
	ds_read2_b32 v[156:157], v153 offset0:158 offset1:223
	s_waitcnt lgkmcnt(0)
	v_cvt_pk_bf16_f32 v139, v156, v157
	global_store_dwordx4 v[158:159], v[136:139], off
	v_add_u32_e32 v158, s5, v149
	v_ashrrev_i32_e32 v159, 31, v158
	v_lshlrev_b64 v[158:159], 12, v[158:159]
	ds_read2_b32 v[156:157], v145 offset0:32 offset1:97
	s_waitcnt lgkmcnt(0)
	v_cvt_pk_bf16_f32 v136, v156, v157
	ds_read2_b32 v[138:139], v145 offset0:162 offset1:227
	v_lshl_add_u64 v[158:159], s[14:15], 0, v[158:159]
	s_waitcnt lgkmcnt(0)
	v_cvt_pk_bf16_f32 v137, v138, v139
	ds_read2_b32 v[138:139], v153 offset0:36 offset1:101
	v_lshl_add_u64 v[158:159], v[158:159], 0, v[154:155]
	s_waitcnt lgkmcnt(0)
	v_cvt_pk_bf16_f32 v138, v138, v139
	ds_read2_b32 v[156:157], v153 offset0:166 offset1:231
	s_waitcnt lgkmcnt(0)
	v_cvt_pk_bf16_f32 v139, v156, v157
	global_store_dwordx4 v[158:159], v[136:139], off
	v_add_u32_e32 v158, s5, v150
	v_ashrrev_i32_e32 v159, 31, v158
	v_lshlrev_b64 v[158:159], 12, v[158:159]
	ds_read2_b32 v[156:157], v145 offset0:40 offset1:105
	s_waitcnt lgkmcnt(0)
	v_cvt_pk_bf16_f32 v136, v156, v157
	ds_read2_b32 v[138:139], v145 offset0:170 offset1:235
	v_lshl_add_u64 v[158:159], s[14:15], 0, v[158:159]
	s_waitcnt lgkmcnt(0)
	v_cvt_pk_bf16_f32 v137, v138, v139
	ds_read2_b32 v[138:139], v153 offset0:44 offset1:109
	v_lshl_add_u64 v[158:159], v[158:159], 0, v[154:155]
	s_waitcnt lgkmcnt(0)
	v_cvt_pk_bf16_f32 v138, v138, v139
	ds_read2_b32 v[156:157], v153 offset0:174 offset1:239
	s_waitcnt lgkmcnt(0)
	v_cvt_pk_bf16_f32 v139, v156, v157
	global_store_dwordx4 v[158:159], v[136:139], off
	v_add_u32_e32 v158, s5, v151
	ds_read2_b32 v[156:157], v145 offset0:48 offset1:113
	s_waitcnt lgkmcnt(0)
	v_cvt_pk_bf16_f32 v136, v156, v157
	ds_read2_b32 v[138:139], v145 offset0:178 offset1:243
	v_ashrrev_i32_e32 v159, 31, v158
	s_waitcnt lgkmcnt(0)
	v_cvt_pk_bf16_f32 v137, v138, v139
	ds_read2_b32 v[138:139], v153 offset0:52 offset1:117
	v_lshlrev_b64 v[158:159], 12, v[158:159]
	s_waitcnt lgkmcnt(0)
	v_cvt_pk_bf16_f32 v138, v138, v139
	ds_read2_b32 v[156:157], v153 offset0:182 offset1:247
	v_lshl_add_u64 v[158:159], s[14:15], 0, v[158:159]
	s_waitcnt lgkmcnt(0)
	v_cvt_pk_bf16_f32 v139, v156, v157
	ds_read2_b32 v[156:157], v145 offset0:56 offset1:121
	v_lshl_add_u64 v[158:159], v[158:159], 0, v[154:155]
	global_store_dwordx4 v[158:159], v[136:139], off
	s_andn2_b64 vcc, exec, s[16:17]
	s_mov_b64 s[16:17], -1
	s_waitcnt lgkmcnt(0)
	v_cvt_pk_bf16_f32 v136, v156, v157
	v_add_u32_e32 v156, s5, v152
	v_ashrrev_i32_e32 v157, 31, v156
	v_lshlrev_b64 v[156:157], 12, v[156:157]
	ds_read2_b32 v[138:139], v145 offset0:186 offset1:251
	v_lshl_add_u64 v[156:157], s[14:15], 0, v[156:157]
	s_waitcnt lgkmcnt(0)
	v_cvt_pk_bf16_f32 v137, v138, v139
	ds_read2_b32 v[138:139], v153 offset0:60 offset1:125
	v_lshl_add_u64 v[154:155], v[156:157], 0, v[154:155]
	s_waitcnt lgkmcnt(0)
	v_cvt_pk_bf16_f32 v138, v138, v139
	ds_read2_b32 v[158:159], v153 offset0:190 offset1:255
	s_waitcnt lgkmcnt(0)
	v_cvt_pk_bf16_f32 v139, v158, v159
	global_store_dwordx4 v[154:155], v[136:139], off
	s_waitcnt lgkmcnt(0)
	s_cbranch_vccnz .LBB0_374
	s_add_i32 s5, s24, s77
	s_cmpk_gt_i32 s5, 0x3ff
	s_cselect_b64 s[16:17], -1, 0
	s_and_b64 vcc, exec, s[16:17]
	s_cbranch_vccnz .LBB0_404
	s_ashr_i32 s6, s5, 31
	s_lshr_b32 s6, s6, 27
	s_add_i32 s6, s5, s6
	s_and_b32 s7, s6, 0xffffffe0
	s_sub_i32 s7, s5, s7
	s_cmp_lt_i32 s7, 0
	s_cbranch_scc1 .LBB0_404
	s_ashr_i32 s6, s6, 5
	s_waitcnt vmcnt(23)
	v_lshl_add_u32 v2, s6, 6, v140
	v_ashrrev_i32_e32 v3, 31, v2
	v_lshlrev_b64 v[2:3], 13, v[2:3]
	s_lshl_b32 s8, s7, 6
	v_lshl_add_u64 v[2:3], s[12:13], 0, v[2:3]
	v_lshl_add_u64 v[2:3], s[8:9], 2, v[2:3]
	s_waitcnt vmcnt(9)
	v_lshl_add_u64 v[66:67], v[132:133], 2, v[2:3]
	v_add_co_u32_e32 v6, vcc, 0x8000, v66
	s_nop 1
	v_addc_co_u32_e32 v7, vcc, 0, v67, vcc
	v_add_co_u32_e32 v10, vcc, 0x10000, v66
	global_load_dwordx4 v[2:5], v[66:67], off nt
	s_nop 0
	global_load_dwordx4 v[6:9], v[6:7], off nt
	v_addc_co_u32_e32 v11, vcc, 0, v67, vcc
	v_add_co_u32_e32 v14, vcc, 0x18000, v66
	s_nop 1
	v_addc_co_u32_e32 v15, vcc, 0, v67, vcc
	v_add_co_u32_e32 v18, vcc, s45, v66
	global_load_dwordx4 v[10:13], v[10:11], off nt
	s_nop 0
	global_load_dwordx4 v[14:17], v[14:15], off nt
	v_addc_co_u32_e32 v19, vcc, 0, v67, vcc
	v_add_co_u32_e32 v22, vcc, 0x28000, v66
	s_nop 1
	v_addc_co_u32_e32 v23, vcc, 0, v67, vcc
	v_add_co_u32_e32 v26, vcc, 0x30000, v66
	global_load_dwordx4 v[18:21], v[18:19], off nt
	s_nop 0
	global_load_dwordx4 v[22:25], v[22:23], off nt
	v_addc_co_u32_e32 v27, vcc, 0, v67, vcc
	v_add_co_u32_e32 v30, vcc, 0x38000, v66
	s_nop 1
	v_addc_co_u32_e32 v31, vcc, 0, v67, vcc
	v_add_co_u32_e32 v34, vcc, 0x40000, v66
	global_load_dwordx4 v[26:29], v[26:27], off nt
	s_nop 0
	global_load_dwordx4 v[30:33], v[30:31], off nt
	v_addc_co_u32_e32 v35, vcc, 0, v67, vcc
	v_add_co_u32_e32 v38, vcc, 0x48000, v66
	s_nop 1
	v_addc_co_u32_e32 v39, vcc, 0, v67, vcc
	v_add_co_u32_e32 v42, vcc, 0x50000, v66
	global_load_dwordx4 v[34:37], v[34:35], off nt
	s_nop 0
	global_load_dwordx4 v[38:41], v[38:39], off nt
	v_addc_co_u32_e32 v43, vcc, 0, v67, vcc
	v_add_co_u32_e32 v46, vcc, 0x58000, v66
	s_nop 1
	v_addc_co_u32_e32 v47, vcc, 0, v67, vcc
	v_add_co_u32_e32 v50, vcc, 0x60000, v66
	global_load_dwordx4 v[42:45], v[42:43], off nt
	s_nop 0
	global_load_dwordx4 v[46:49], v[46:47], off nt
	v_addc_co_u32_e32 v51, vcc, 0, v67, vcc
	v_add_co_u32_e32 v54, vcc, 0x68000, v66
	s_nop 1
	v_addc_co_u32_e32 v55, vcc, 0, v67, vcc
	v_add_co_u32_e32 v68, vcc, 0x70000, v66
	global_load_dwordx4 v[50:53], v[50:51], off nt
	s_nop 0
	global_load_dwordx4 v[54:57], v[54:55], off nt
	v_addc_co_u32_e32 v69, vcc, 0, v67, vcc
	s_waitcnt vmcnt(22)
	v_add_co_u32_e32 v70, vcc, 0x78000, v66
	s_nop 1
	v_addc_co_u32_e32 v71, vcc, 0, v67, vcc
	global_load_dwordx4 v[66:69], v[68:69], off nt
	s_nop 0
	global_load_dwordx4 v[70:73], v[70:71], off nt

.LBB0_431:
	s_waitcnt lgkmcnt(0)
	v_lshl_add_u64 v[30:31], s[16:17], 0, v[54:55]
	global_load_dwordx4 v[26:29], v[30:31], off offset:16 nt
	s_nop 0
	global_load_dwordx4 v[30:33], v[30:31], off nt
	v_lshl_add_u64 v[74:75], v[48:49], 0, s[18:19]
	v_cmp_gt_u64_e32 vcc, s[30:31], v[74:75]
	s_and_saveexec_b64 s[6:7], vcc
	s_cbranch_execz .LBB0_433
	v_lshl_add_u64 v[2:3], s[16:17], 0, v[50:51]
	global_load_dwordx4 v[10:13], v[2:3], off offset:16 nt
	s_nop 0
	global_load_dwordx4 v[2:5], v[2:3], off nt
.LBB0_433:
	s_or_b64 exec, exec, s[6:7]
	v_lshl_add_u64 v[76:77], v[58:59], 0, s[18:19]
	v_cmp_gt_u64_e64 s[6:7], s[30:31], v[76:77]
	s_and_saveexec_b64 s[8:9], s[6:7]
	s_cbranch_execz .LBB0_435
	v_lshl_add_u64 v[6:7], s[16:17], 0, v[62:63]
	global_load_dwordx4 v[18:21], v[6:7], off nt
	s_nop 0
	global_load_dwordx4 v[6:9], v[6:7], off offset:-16 nt
.LBB0_435:
	s_or_b64 exec, exec, s[8:9]
	v_lshl_add_u64 v[78:79], v[66:67], 0, s[18:19]
	v_cmp_gt_u64_e64 s[8:9], s[30:31], v[78:79]
	s_and_saveexec_b64 s[36:37], s[8:9]
	s_cbranch_execz .LBB0_437
	v_lshl_add_u64 v[14:15], s[16:17], 0, v[68:69]
	global_load_dwordx4 v[22:25], v[14:15], off nt
	s_nop 0
	global_load_dwordx4 v[14:17], v[14:15], off offset:-16 nt

.LBB0_447:
	s_waitcnt lgkmcnt(0)
	v_lshl_add_u64 v[30:31], s[16:17], 0, v[58:59]
	global_load_dwordx4 v[26:29], v[30:31], off offset:16 nt
	s_nop 0
	global_load_dwordx4 v[30:33], v[30:31], off nt
	v_lshl_add_u64 v[76:77], v[52:53], 0, s[18:19]
	v_cmp_gt_u64_e32 vcc, s[10:11], v[76:77]
	s_and_saveexec_b64 s[6:7], vcc
	s_cbranch_execz .LBB0_449
	v_lshl_add_u64 v[2:3], s[16:17], 0, v[54:55]
	global_load_dwordx4 v[10:13], v[2:3], off offset:16 nt
	s_nop 0
	global_load_dwordx4 v[2:5], v[2:3], off nt
.LBB0_449:
	s_or_b64 exec, exec, s[6:7]
	v_lshl_add_u64 v[76:77], v[64:65], 0, s[18:19]
	v_cmp_gt_u64_e64 s[6:7], s[10:11], v[76:77]
	s_and_saveexec_b64 s[8:9], s[6:7]
	s_cbranch_execz .LBB0_451
	v_lshl_add_u64 v[6:7], s[16:17], 0, v[68:69]
	global_load_dwordx4 v[18:21], v[6:7], off nt
	s_nop 0
	global_load_dwordx4 v[6:9], v[6:7], off offset:-16 nt
.LBB0_451:
	s_or_b64 exec, exec, s[8:9]
	v_lshl_add_u64 v[76:77], v[72:73], 0, s[18:19]
	v_cmp_gt_u64_e64 s[8:9], s[10:11], v[76:77]
	s_and_saveexec_b64 s[34:35], s[8:9]
	s_cbranch_execz .LBB0_453
	v_lshl_add_u64 v[14:15], s[16:17], 0, v[66:67]
	global_load_dwordx4 v[22:25], v[14:15], off offset:16 nt
	s_nop 0
	global_load_dwordx4 v[14:17], v[14:15], off nt

.LBB0_462:
	s_waitcnt lgkmcnt(0)
	v_lshl_add_u64 v[30:31], s[18:19], 0, v[46:47]
	global_load_dwordx4 v[26:29], v[30:31], off offset:16 nt
	s_nop 0
	global_load_dwordx4 v[30:33], v[30:31], off nt
	v_lshl_add_u64 v[74:75], v[52:53], 0, s[20:21]
	v_cmp_gt_u64_e64 s[6:7], s[14:15], v[74:75]
	s_and_saveexec_b64 s[8:9], s[6:7]
	s_cbranch_execz .LBB0_464
	v_lshl_add_u64 v[2:3], s[18:19], 0, v[54:55]
	global_load_dwordx4 v[10:13], v[2:3], off offset:16 nt
	s_nop 0
	global_load_dwordx4 v[2:5], v[2:3], off nt
.LBB0_464:
	s_or_b64 exec, exec, s[8:9]
	v_lshl_add_u64 v[74:75], v[62:63], 0, s[20:21]
	v_cmp_gt_u64_e64 s[8:9], s[14:15], v[74:75]
	s_and_saveexec_b64 s[10:11], s[8:9]
	s_cbranch_execz .LBB0_466
	v_lshl_add_u64 v[6:7], s[18:19], 0, v[66:67]
	global_load_dwordx4 v[18:21], v[6:7], off nt
	s_nop 0
	global_load_dwordx4 v[6:9], v[6:7], off offset:-16 nt
.LBB0_466:
	s_or_b64 exec, exec, s[10:11]
	v_lshl_add_u64 v[74:75], v[70:71], 0, s[20:21]
	v_cmp_gt_u64_e64 s[10:11], s[14:15], v[74:75]
	s_and_saveexec_b64 s[36:37], s[10:11]
	s_cbranch_execz .LBB0_468
	v_lshl_add_u64 v[14:15], s[18:19], 0, v[64:65]
	global_load_dwordx4 v[22:25], v[14:15], off offset:16 nt
	s_nop 0
	global_load_dwordx4 v[14:17], v[14:15], off nt

.LBB0_477:
	s_waitcnt lgkmcnt(0)
	v_lshl_add_u64 v[26:27], s[16:17], 0, v[36:37]
	v_lshl_add_u64 v[30:31], v[26:27], 0, s[26:27]
	v_add_co_u32_e32 v26, vcc, s2, v26
	v_lshl_add_u64 v[60:61], v[48:49], 0, s[12:13]
	s_nop 0
	v_addc_co_u32_e32 v27, vcc, 0, v27, vcc
	global_load_dwordx4 v[26:29], v[26:27], off nt
	s_nop 0
	global_load_dwordx4 v[30:33], v[30:31], off offset:16 nt
	v_cmp_gt_u64_e64 s[6:7], s[28:29], v[60:61]
	s_and_saveexec_b64 s[8:9], s[6:7]
	s_cbranch_execz .LBB0_479
	v_lshl_add_u64 v[2:3], s[16:17], 0, v[58:59]
	v_lshl_add_u64 v[14:15], v[2:3], 0, s[26:27]
	v_add_co_u32_e32 v2, vcc, 0x1000000, v2
	s_nop 1
	v_addc_co_u32_e32 v3, vcc, 0, v3, vcc
	global_load_dwordx4 v[2:5], v[2:3], off nt
	s_nop 0
	global_load_dwordx4 v[14:17], v[14:15], off offset:16 nt
.LBB0_479:
	s_or_b64 exec, exec, s[8:9]
	v_lshl_add_u64 v[60:61], v[46:47], 0, s[12:13]
	v_cmp_gt_u64_e64 s[8:9], s[28:29], v[60:61]
	s_and_saveexec_b64 s[10:11], s[8:9]
	s_cbranch_execz .LBB0_481
	v_lshl_add_u64 v[6:7], s[16:17], 0, v[52:53]
	v_lshl_add_u64 v[18:19], v[6:7], 0, s[26:27]
	v_add_co_u32_e32 v6, vcc, 0x1000000, v6
	s_nop 1
	v_addc_co_u32_e32 v7, vcc, 0, v7, vcc
	global_load_dwordx4 v[6:9], v[6:7], off nt
	s_nop 0
	global_load_dwordx4 v[18:21], v[18:19], off offset:16 nt
.LBB0_481:
	s_or_b64 exec, exec, s[10:11]
	v_lshl_add_u64 v[60:61], v[56:57], 0, s[12:13]
	v_cmp_gt_u64_e64 s[10:11], s[28:29], v[60:61]
	s_and_saveexec_b64 s[36:37], s[10:11]
	s_cbranch_execz .LBB0_483
	v_lshl_add_u64 v[10:11], s[16:17], 0, v[50:51]
	v_lshl_add_u64 v[22:23], v[10:11], 0, s[26:27]
	v_add_co_u32_e32 v10, vcc, 0x1000000, v10
	s_nop 1
	v_addc_co_u32_e32 v11, vcc, 0, v11, vcc
	global_load_dwordx4 v[10:13], v[10:11], off nt
	s_nop 0
	global_load_dwordx4 v[22:25], v[22:23], off offset:16 nt
